# merge_scale hooks: gate loads of four groups prefetched per batch (two batches per hook)
# speedup vs baseline: 1.0256x; 1.0066x over previous
; #define STAGE(P, BASE, br, kt) do { const bf16_t* g_ = (BASE) + (size_t)(br) * K + (size_t)(kt) * 64; \
;         _Pragma("unroll") for (int i_ = 0; i_ < 2; ++i_) \
;             __builtin_amdgcn_global_load_lds((const unsigned*)(g_ + gofs[i_]), (lds_ptr_t)((P) + wb + i_ * 8192), 16, 0, 0); } while (0)
; #define LDA(dst, b, hh) _Pragma("unroll") for (int m = 0; m < 4; ++m) _Pragma("unroll") for (int k = 0; k < 2; ++k) \
;         dst[m][k] = *(const bf16x8*)(SA(b, hh) + lds_byte(wr * 64 + m * 16 + fr, k * 32 + fq * 8))
; #define LDB(dst, b, hh) _Pragma("unroll") for (int n = 0; n < 2; ++n) _Pragma("unroll") for (int k = 0; k < 2; ++k) \
;         dst[n][k] = *(const bf16x8*)(SB(b, hh) + lds_byte(wc * 32 + n * 16 + fr, k * 32 + fq * 8))
; #define MMA(ai, bj, At_, Bt_) do { __builtin_amdgcn_s_setprio(1); \
;         _Pragma("unroll") for (int m = 0; m < 4; ++m) _Pragma("unroll") for (int n = 0; n < 2; ++n) _Pragma("unroll") for (int k = 0; k < 2; ++k) \
;             acc[ai][bj][m][n] = MFMA16(At_[m][k], Bt_[n][k], acc[ai][bj][m][n]); \
;         __builtin_amdgcn_s_setprio(0); } while (0)
; #define WAIT_V(n) asm volatile("s_waitcnt vmcnt(" #n ")" ::: "memory")
; #define BAR __builtin_amdgcn_s_barrier()
; template <class Hook>
; DI void gemm8_cat3(f32x4 (&acc)[2][2][4][2], const bf16_t* R0, const bf16_t* R1, const bf16_t* R2, const bf16_t* C0, const bf16_t* C1, const bf16_t* C2, char* shm, Hook hook) {
;     ...
;     for (int tt = 0; tt < 8; tt += 2) {
;         LDB(B0, 0, 0); SCHED; LDA(At, 0, 0); STAGE(SA(1, 1), R, 128, tt + 1);
;         WAIT_L(8); BAR; WAIT_L(0); MMA(0, 0, At, B0); BAR; SCHED;
;         LDB(B1, 0, 1); STAGE(SB(0, 0), C, 0, tt + 2);
;         BAR; WAIT_L(0); MMA(0, 1, At, B1); BAR;
;         LDA(At, 0, 1); STAGE(SA(0, 0), R, 0, tt + 2);
;         BAR; WAIT_L(0); MMA(1, 0, At, B0); BAR; SCHED;
;         STAGE(SB(0, 1), C, 128, tt + 2);
;         WAIT_V(6); BAR; MMA(1, 1, At, B1); BAR;
;         LDB(B0, 1, 0); SCHED; LDA(At, 1, 0); STAGE(SA(0, 1), R, 128, tt + 2);
;         WAIT_L(8); BAR; WAIT_L(0); MMA(0, 0, At, B0); BAR; SCHED;
;         LDB(B1, 1, 1); STAGE(SB(1, 0), C, 0, tt + 3);
;         BAR; WAIT_L(0); MMA(0, 1, At, B1); BAR;
;         LDA(At, 1, 1); STAGE(SA(1, 0), R, 0, tt + 3);
;         BAR; WAIT_L(0); MMA(1, 0, At, B0); BAR; SCHED;
;         STAGE(SB(1, 1), C, 128, tt + 3);
;         WAIT_V(6); BAR; MMA(1, 1, At, B1); BAR;
;     }
.LBB0_56:
	ds_read_b128 v[150:153], v189
	ds_read_b128 v[192:195], v189 offset:1024
	ds_read_b128 v[196:199], v189 offset:2048
	ds_read_b128 v[200:203], v189 offset:3072
	v_add_u32_e32 v190, 0xc000, v158
	v_add_u32_e32 v191, 0xe000, v158
	v_readfirstlane_b32 s7, v190
	s_mov_b32 m0, s7
	v_readfirstlane_b32 s7, v191
	ds_read_b128 v[204:207], v157
	ds_read_b128 v[208:211], v157 offset:1024
	ds_read_b128 v[212:215], v156
	ds_read_b128 v[216:219], v156 offset:1024
	ds_read_b128 v[220:223], v155
	ds_read_b128 v[224:227], v155 offset:1024
	ds_read_b128 v[228:231], v154
	ds_read_b128 v[232:235], v154 offset:1024
	global_load_lds_dwordx4 v[130:131], off
	s_mov_b32 m0, s7
	s_nop 0
	global_load_lds_dwordx4 v[132:133], off
	s_waitcnt lgkmcnt(8)
	s_barrier
	s_waitcnt lgkmcnt(0)
	s_setprio 1
	s_waitcnt lgkmcnt(0)
	v_mfma_f32_16x16x32_bf16 v[18:21], v[204:207], v[150:153], v[18:21]
	v_mfma_f32_16x16x32_bf16 v[58:61], v[204:207], v[196:199], v[58:61]
	v_mfma_f32_16x16x32_bf16 v[30:33], v[212:215], v[150:153], v[30:33]
	v_mfma_f32_16x16x32_bf16 v[54:57], v[212:215], v[196:199], v[54:57]
	v_mfma_f32_16x16x32_bf16 v[26:29], v[220:223], v[150:153], v[26:29]
	v_mfma_f32_16x16x32_bf16 v[50:53], v[220:223], v[196:199], v[50:53]
	v_mfma_f32_16x16x32_bf16 v[42:45], v[228:231], v[150:153], v[42:45]
	v_mfma_f32_16x16x32_bf16 v[46:49], v[228:231], v[196:199], v[46:49]
	v_mfma_f32_16x16x32_bf16 v[18:21], v[208:211], v[192:195], v[18:21]
	v_mfma_f32_16x16x32_bf16 v[58:61], v[208:211], v[200:203], v[58:61]
	v_mfma_f32_16x16x32_bf16 v[30:33], v[216:219], v[192:195], v[30:33]
	v_mfma_f32_16x16x32_bf16 v[54:57], v[216:219], v[200:203], v[54:57]
	v_mfma_f32_16x16x32_bf16 v[26:29], v[224:227], v[192:195], v[26:29]
	v_mfma_f32_16x16x32_bf16 v[50:53], v[224:227], v[200:203], v[50:53]
	v_mfma_f32_16x16x32_bf16 v[42:45], v[232:235], v[192:195], v[42:45]
	v_mfma_f32_16x16x32_bf16 v[46:49], v[232:235], v[200:203], v[46:49]
	s_setprio 0
	s_barrier
	s_add_i32 s7, s6, 2
	s_cmp_lt_u32 s6, 6
	s_cselect_b64 s[16:17], -1, 0
	s_and_b64 s[20:21], s[16:17], exec
	s_cselect_b32 s21, s11, s82
	s_cselect_b32 s20, s10, s25
	s_and_b32 s22, s2, 0x180
	s_lshl_b32 s22, s22, 1
	s_add_u32 s20, s20, s22
	s_addc_u32 s21, s21, 0
	v_readfirstlane_b32 s23, v159
	v_lshl_add_u64 v[172:173], s[20:21], 0, v[134:135]
	s_mov_b32 m0, s23
	v_readfirstlane_b32 s23, v160
	ds_read_b128 v[236:239], v188
	ds_read_b128 v[240:243], v188 offset:1024
	ds_read_b128 v[244:247], v188 offset:2048
	ds_read_b128 v[248:251], v188 offset:3072
	global_load_lds_dwordx4 v[172:173], off
	v_lshl_add_u64 v[172:173], s[20:21], 0, v[136:137]
	s_mov_b32 m0, s23
	s_nop 0
	global_load_lds_dwordx4 v[172:173], off
	s_barrier
	s_waitcnt lgkmcnt(0)
	s_setprio 1
	s_waitcnt lgkmcnt(0)
	v_mfma_f32_16x16x32_bf16 v[74:77], v[204:207], v[236:239], v[74:77]
	v_mfma_f32_16x16x32_bf16 v[90:93], v[204:207], v[244:247], v[90:93]
	v_mfma_f32_16x16x32_bf16 v[70:73], v[212:215], v[236:239], v[70:73]
	v_mfma_f32_16x16x32_bf16 v[86:89], v[212:215], v[244:247], v[86:89]
	v_mfma_f32_16x16x32_bf16 v[66:69], v[220:223], v[236:239], v[66:69]
	v_mfma_f32_16x16x32_bf16 v[82:85], v[220:223], v[244:247], v[82:85]
	v_mfma_f32_16x16x32_bf16 v[62:65], v[228:231], v[236:239], v[62:65]
	v_mfma_f32_16x16x32_bf16 v[78:81], v[228:231], v[244:247], v[78:81]
	v_mfma_f32_16x16x32_bf16 v[74:77], v[208:211], v[240:243], v[74:77]
	v_mfma_f32_16x16x32_bf16 v[90:93], v[208:211], v[248:251], v[90:93]
	v_mfma_f32_16x16x32_bf16 v[70:73], v[216:219], v[240:243], v[70:73]
	v_mfma_f32_16x16x32_bf16 v[86:89], v[216:219], v[248:251], v[86:89]
	v_mfma_f32_16x16x32_bf16 v[66:69], v[224:227], v[240:243], v[66:69]
	v_mfma_f32_16x16x32_bf16 v[82:85], v[224:227], v[248:251], v[82:85]
	v_mfma_f32_16x16x32_bf16 v[62:65], v[232:235], v[240:243], v[62:65]
	v_mfma_f32_16x16x32_bf16 v[78:81], v[232:235], v[248:251], v[78:81]
	s_setprio 0
	s_and_b64 vcc, s[16:17], exec
	s_cselect_b32 s16, s8, s15
	s_cselect_b32 s17, s9, s24
	s_add_u32 s16, s16, s22
	s_addc_u32 s17, s17, 0
	v_readfirstlane_b32 s22, v158
	v_lshl_add_u64 v[172:173], s[16:17], 0, v[134:135]
	s_mov_b32 m0, s22
	v_readfirstlane_b32 s22, v164
	s_barrier
	ds_read_b128 v[204:207], v157 offset:16384
	ds_read_b128 v[208:211], v157 offset:17408
	ds_read_b128 v[212:215], v156 offset:16384
	ds_read_b128 v[216:219], v156 offset:17408
	ds_read_b128 v[220:223], v155 offset:16384
	ds_read_b128 v[224:227], v155 offset:17408
	ds_read_b128 v[228:231], v154 offset:16384
	ds_read_b128 v[232:235], v154 offset:17408
	global_load_lds_dwordx4 v[172:173], off
	v_lshl_add_u64 v[172:173], s[16:17], 0, v[136:137]
	s_mov_b32 m0, s22
	s_nop 0
	global_load_lds_dwordx4 v[172:173], off
	s_barrier
	s_waitcnt lgkmcnt(0)
	s_setprio 1
	s_waitcnt lgkmcnt(0)
	v_mfma_f32_16x16x32_bf16 v[106:109], v[204:207], v[150:153], v[106:109]
	v_mfma_f32_16x16x32_bf16 v[122:125], v[204:207], v[196:199], v[122:125]
	v_mfma_f32_16x16x32_bf16 v[102:105], v[212:215], v[150:153], v[102:105]
	v_mfma_f32_16x16x32_bf16 v[118:121], v[212:215], v[196:199], v[118:121]
	v_mfma_f32_16x16x32_bf16 v[98:101], v[220:223], v[150:153], v[98:101]
	v_mfma_f32_16x16x32_bf16 v[114:117], v[220:223], v[196:199], v[114:117]
	v_mfma_f32_16x16x32_bf16 v[94:97], v[228:231], v[150:153], v[94:97]
	v_mfma_f32_16x16x32_bf16 v[110:113], v[228:231], v[196:199], v[110:113]
	v_mfma_f32_16x16x32_bf16 v[106:109], v[208:211], v[192:195], v[106:109]
	v_mfma_f32_16x16x32_bf16 v[122:125], v[208:211], v[200:203], v[122:125]
	v_mfma_f32_16x16x32_bf16 v[102:105], v[216:219], v[192:195], v[102:105]
	v_mfma_f32_16x16x32_bf16 v[118:121], v[216:219], v[200:203], v[118:121]
	v_mfma_f32_16x16x32_bf16 v[98:101], v[224:227], v[192:195], v[98:101]
	v_mfma_f32_16x16x32_bf16 v[114:117], v[224:227], v[200:203], v[114:117]
	v_mfma_f32_16x16x32_bf16 v[94:97], v[232:235], v[192:195], v[94:97]
	v_mfma_f32_16x16x32_bf16 v[110:113], v[232:235], v[200:203], v[110:113]
	s_setprio 0
	s_barrier
; #define STAGE(P, BASE, br, kt) do { const bf16_t* g_ = (BASE) + (size_t)(br) * K + (size_t)(kt) * 64; \
;         _Pragma("unroll") for (int i_ = 0; i_ < 2; ++i_) \
;             __builtin_amdgcn_global_load_lds((const unsigned*)(g_ + gofs[i_]), (lds_ptr_t)((P) + wb + i_ * 8192), 16, 0, 0); } while (0)
; #define LDA(dst, b, hh) _Pragma("unroll") for (int m = 0; m < 4; ++m) _Pragma("unroll") for (int k = 0; k < 2; ++k) \
;         dst[m][k] = *(const bf16x8*)(SA(b, hh) + lds_byte(wr * 64 + m * 16 + fr, k * 32 + fq * 8))
; #define LDB(dst, b, hh) _Pragma("unroll") for (int n = 0; n < 2; ++n) _Pragma("unroll") for (int k = 0; k < 2; ++k) \
;         dst[n][k] = *(const bf16x8*)(SB(b, hh) + lds_byte(wc * 32 + n * 16 + fr, k * 32 + fq * 8))
; #define MMA(ai, bj, At_, Bt_) do { __builtin_amdgcn_s_setprio(1); \
;         _Pragma("unroll") for (int m = 0; m < 4; ++m) _Pragma("unroll") for (int n = 0; n < 2; ++n) _Pragma("unroll") for (int k = 0; k < 2; ++k) \
;             acc[ai][bj][m][n] = MFMA16(At_[m][k], Bt_[n][k], acc[ai][bj][m][n]); \
;         __builtin_amdgcn_s_setprio(0); } while (0)
; #define WAIT_V(n) asm volatile("s_waitcnt vmcnt(" #n ")" ::: "memory")
; #define WAIT_L(n) asm volatile("s_waitcnt lgkmcnt(" #n ")" ::: "memory")
; #define BAR __builtin_amdgcn_s_barrier()
; #define SCHED __builtin_amdgcn_sched_barrier(0)
; #define WAIT_V(n) asm volatile("s_waitcnt vmcnt(" #n ")" ::: "memory")
; #define WAIT_L(n) asm volatile("s_waitcnt lgkmcnt(" #n ")" ::: "memory")
; template <class Hook>
; DI void gemm8_cat3(f32x4 (&acc)[2][2][4][2], const bf16_t* R0, const bf16_t* R1, const bf16_t* R2, const bf16_t* C0, const bf16_t* C1, const bf16_t* C2, char* shm, Hook hook) {
;     ...
;         LDA(At, 0, 1); STAGE(SA(0, 0), R, 0, tt + 2);
;         BAR; WAIT_L(0); MMA(1, 0, At, B0); BAR; SCHED;
;         STAGE(SB(0, 1), C, 128, tt + 2);
;         WAIT_V(6); BAR; MMA(1, 1, At, B1); BAR;
;         LDB(B0, 1, 0); SCHED; LDA(At, 1, 0); STAGE(SA(0, 1), R, 128, tt + 2);
;         WAIT_L(8); BAR; WAIT_L(0); MMA(0, 0, At, B0); BAR; SCHED;
;         LDB(B1, 1, 1); STAGE(SB(1, 0), C, 0, tt + 3);
;         BAR; WAIT_L(0); MMA(0, 1, At, B1); BAR;
;         LDA(At, 1, 1); STAGE(SA(1, 0), R, 0, tt + 3);
;         BAR; WAIT_L(0); MMA(1, 0, At, B0); BAR; SCHED;
;         STAGE(SB(1, 1), C, 128, tt + 3);
;         WAIT_V(6); BAR; MMA(1, 1, At, B1); BAR;
	s_add_u32 s20, s20, 0x20000
	s_addc_u32 s21, s21, 0
	v_readfirstlane_b32 s22, v165
	v_lshl_add_u64 v[150:151], s[20:21], 0, v[134:135]
	s_mov_b32 m0, s22
	s_nop 0
	global_load_lds_dwordx4 v[150:151], off
	v_lshl_add_u64 v[150:151], s[20:21], 0, v[136:137]
	v_readfirstlane_b32 s20, v166
	s_mov_b32 m0, s20
	s_nop 0
	global_load_lds_dwordx4 v[150:151], off
	s_waitcnt vmcnt(6)
	s_barrier
	s_setprio 1
	v_mfma_f32_16x16x32_bf16 v[126:129], v[204:207], v[236:239], v[126:129]
	v_mfma_f32_16x16x32_bf16 v[14:17], v[204:207], v[244:247], v[14:17]
	v_mfma_f32_16x16x32_bf16 v[34:37], v[212:215], v[236:239], v[34:37]
	v_mfma_f32_16x16x32_bf16 v[6:9], v[212:215], v[244:247], v[6:9]
	v_mfma_f32_16x16x32_bf16 v[38:41], v[220:223], v[236:239], v[38:41]
	v_mfma_f32_16x16x32_bf16 v[10:13], v[220:223], v[244:247], v[10:13]
	v_mfma_f32_16x16x32_bf16 v[22:25], v[228:231], v[236:239], v[22:25]
	v_mfma_f32_16x16x32_bf16 v[2:5], v[228:231], v[244:247], v[2:5]
	v_mfma_f32_16x16x32_bf16 v[126:129], v[208:211], v[240:243], v[126:129]
	v_mfma_f32_16x16x32_bf16 v[14:17], v[208:211], v[248:251], v[14:17]
	v_mfma_f32_16x16x32_bf16 v[34:37], v[216:219], v[240:243], v[34:37]
	v_mfma_f32_16x16x32_bf16 v[6:9], v[216:219], v[248:251], v[6:9]
	v_mfma_f32_16x16x32_bf16 v[38:41], v[224:227], v[240:243], v[38:41]
	v_mfma_f32_16x16x32_bf16 v[10:13], v[224:227], v[248:251], v[10:13]
	v_mfma_f32_16x16x32_bf16 v[22:25], v[232:235], v[240:243], v[22:25]
	v_mfma_f32_16x16x32_bf16 v[2:5], v[232:235], v[248:251], v[2:5]
	s_setprio 0
	s_barrier
	ds_read_b128 v[150:153], v169
	ds_read_b128 v[192:195], v169 offset:1024
	ds_read_b128 v[196:199], v169 offset:2048
	ds_read_b128 v[200:203], v169 offset:3072
	s_add_u32 s16, s16, 0x20000
	s_addc_u32 s17, s17, 0
	v_readfirstlane_b32 s20, v167
	v_lshl_add_u64 v[172:173], s[16:17], 0, v[134:135]
	s_mov_b32 m0, s20
	ds_read_b128 v[204:207], v157 offset:32768
	ds_read_b128 v[208:211], v157 offset:33792
	ds_read_b128 v[212:215], v156 offset:32768
	ds_read_b128 v[216:219], v156 offset:33792
	ds_read_b128 v[220:223], v155 offset:32768
	ds_read_b128 v[224:227], v155 offset:33792
	ds_read_b128 v[228:231], v154 offset:32768
	ds_read_b128 v[232:235], v154 offset:33792
	global_load_lds_dwordx4 v[172:173], off
	v_lshl_add_u64 v[172:173], s[16:17], 0, v[136:137]
	v_readfirstlane_b32 s16, v168
	s_mov_b32 m0, s16
	s_nop 0
	global_load_lds_dwordx4 v[172:173], off
	s_waitcnt lgkmcnt(8)
	s_barrier
	s_waitcnt lgkmcnt(0)
	s_setprio 1
	s_waitcnt lgkmcnt(0)
	v_mfma_f32_16x16x32_bf16 v[18:21], v[204:207], v[150:153], v[18:21]
	v_mfma_f32_16x16x32_bf16 v[58:61], v[204:207], v[196:199], v[58:61]
	v_mfma_f32_16x16x32_bf16 v[30:33], v[212:215], v[150:153], v[30:33]
	v_mfma_f32_16x16x32_bf16 v[54:57], v[212:215], v[196:199], v[54:57]
	v_mfma_f32_16x16x32_bf16 v[26:29], v[220:223], v[150:153], v[26:29]
	v_mfma_f32_16x16x32_bf16 v[50:53], v[220:223], v[196:199], v[50:53]
	v_mfma_f32_16x16x32_bf16 v[42:45], v[228:231], v[150:153], v[42:45]
	v_mfma_f32_16x16x32_bf16 v[46:49], v[228:231], v[196:199], v[46:49]
	v_mfma_f32_16x16x32_bf16 v[18:21], v[208:211], v[192:195], v[18:21]
	v_mfma_f32_16x16x32_bf16 v[58:61], v[208:211], v[200:203], v[58:61]
	v_mfma_f32_16x16x32_bf16 v[30:33], v[216:219], v[192:195], v[30:33]
	v_mfma_f32_16x16x32_bf16 v[54:57], v[216:219], v[200:203], v[54:57]
	v_mfma_f32_16x16x32_bf16 v[26:29], v[224:227], v[192:195], v[26:29]
	v_mfma_f32_16x16x32_bf16 v[50:53], v[224:227], v[200:203], v[50:53]
	v_mfma_f32_16x16x32_bf16 v[42:45], v[232:235], v[192:195], v[42:45]
	v_mfma_f32_16x16x32_bf16 v[46:49], v[232:235], v[200:203], v[46:49]
	s_setprio 0
	s_barrier
	s_add_i32 s16, s2, 64
	s_and_b32 s16, s16, 0x1c0
	s_lshl_b32 s20, s16, 1
	s_cmp_lt_u32 s6, 5
	s_cselect_b32 s16, s10, s25
	s_cselect_b32 s6, s11, s82
	s_cselect_b32 s21, s9, s24
	s_cselect_b32 s22, s8, s15
	s_add_u32 s16, s16, s20
	s_addc_u32 s17, s6, 0
	v_readfirstlane_b32 s6, v170
	v_lshl_add_u64 v[172:173], s[16:17], 0, v[134:135]
	s_mov_b32 m0, s6
	v_readfirstlane_b32 s6, v171
	ds_read_b128 v[236:239], v161
	ds_read_b128 v[240:243], v161 offset:1024
	ds_read_b128 v[244:247], v161 offset:2048
	ds_read_b128 v[248:251], v161 offset:3072
	global_load_lds_dwordx4 v[172:173], off
	v_lshl_add_u64 v[172:173], s[16:17], 0, v[136:137]
	s_mov_b32 m0, s6
	s_nop 0
	global_load_lds_dwordx4 v[172:173], off
	s_barrier
	s_waitcnt lgkmcnt(0)
	s_setprio 1
	s_waitcnt lgkmcnt(0)
	v_mfma_f32_16x16x32_bf16 v[74:77], v[204:207], v[236:239], v[74:77]
	v_mfma_f32_16x16x32_bf16 v[90:93], v[204:207], v[244:247], v[90:93]
	v_mfma_f32_16x16x32_bf16 v[70:73], v[212:215], v[236:239], v[70:73]
	v_mfma_f32_16x16x32_bf16 v[86:89], v[212:215], v[244:247], v[86:89]
	v_mfma_f32_16x16x32_bf16 v[66:69], v[220:223], v[236:239], v[66:69]
	v_mfma_f32_16x16x32_bf16 v[82:85], v[220:223], v[244:247], v[82:85]
	v_mfma_f32_16x16x32_bf16 v[62:65], v[228:231], v[236:239], v[62:65]
	v_mfma_f32_16x16x32_bf16 v[78:81], v[228:231], v[244:247], v[78:81]
	v_mfma_f32_16x16x32_bf16 v[74:77], v[208:211], v[240:243], v[74:77]
	v_mfma_f32_16x16x32_bf16 v[90:93], v[208:211], v[248:251], v[90:93]
	v_mfma_f32_16x16x32_bf16 v[70:73], v[216:219], v[240:243], v[70:73]
	v_mfma_f32_16x16x32_bf16 v[86:89], v[216:219], v[248:251], v[86:89]
	v_mfma_f32_16x16x32_bf16 v[66:69], v[224:227], v[240:243], v[66:69]
	v_mfma_f32_16x16x32_bf16 v[82:85], v[224:227], v[248:251], v[82:85]
	v_mfma_f32_16x16x32_bf16 v[62:65], v[232:235], v[240:243], v[62:65]
	v_mfma_f32_16x16x32_bf16 v[78:81], v[232:235], v[248:251], v[78:81]
	s_setprio 0
	s_add_u32 s20, s22, s20
	s_addc_u32 s21, s21, 0
	v_readfirstlane_b32 s6, v184
	v_lshl_add_u64 v[172:173], s[20:21], 0, v[134:135]
	s_mov_b32 m0, s6
	v_readfirstlane_b32 s6, v185
	s_barrier
; DI float frcp(float x) { return __builtin_amdgcn_rcpf(x); }
; #define STAGE(P, BASE, br, kt) do { const bf16_t* g_ = (BASE) + (size_t)(br) * K + (size_t)(kt) * 64; \
;         _Pragma("unroll") for (int i_ = 0; i_ < 2; ++i_) \
;             __builtin_amdgcn_global_load_lds((const unsigned*)(g_ + gofs[i_]), (lds_ptr_t)((P) + wb + i_ * 8192), 16, 0, 0); } while (0)
; #define LDA(dst, b, hh) _Pragma("unroll") for (int m = 0; m < 4; ++m) _Pragma("unroll") for (int k = 0; k < 2; ++k) \
;         dst[m][k] = *(const bf16x8*)(SA(b, hh) + lds_byte(wr * 64 + m * 16 + fr, k * 32 + fq * 8))
; #define MMA(ai, bj, At_, Bt_) do { __builtin_amdgcn_s_setprio(1); \
;         _Pragma("unroll") for (int m = 0; m < 4; ++m) _Pragma("unroll") for (int n = 0; n < 2; ++n) _Pragma("unroll") for (int k = 0; k < 2; ++k) \
;             acc[ai][bj][m][n] = MFMA16(At_[m][k], Bt_[n][k], acc[ai][bj][m][n]); \
;         __builtin_amdgcn_s_setprio(0); } while (0)
; #define WAIT_V(n) asm volatile("s_waitcnt vmcnt(" #n ")" ::: "memory")
; #define WAIT_L(n) asm volatile("s_waitcnt lgkmcnt(" #n ")" ::: "memory")
; #define BAR __builtin_amdgcn_s_barrier()
; template <class Hook>
; DI void gemm8_cat3(f32x4 (&acc)[2][2][4][2], const bf16_t* R0, const bf16_t* R1, const bf16_t* R2, const bf16_t* C0, const bf16_t* C1, const bf16_t* C2, char* shm, Hook hook) {
;     ...
;         LDA(At, 1, 1); STAGE(SA(1, 0), R, 0, tt + 3);
;         BAR; WAIT_L(0); MMA(1, 0, At, B0); BAR; SCHED;
;         STAGE(SB(1, 1), C, 128, tt + 3);
;         WAIT_V(6); BAR; MMA(1, 1, At, B1); BAR;
;     }
;     hook(0);
; DI void merge_scale(const Params& P, int tile, int seg, f32x4 (&acc)[2][2][4][2]) {
; #pragma unroll
;     for (int g8 = 0; g8 < 8; ++g8) {
;         const int ai = g8 >> 2, bj = (g8 >> 1) & 1, nn = g8 & 1;
;         const u32x4 ga = *gate_slot(P, tile, seg, g8), gb = *gate_slot(P, tile, seg + 1, g8);
; #pragma unroll
;         for (int e = 0; e < 8; ++e) {
;             const float rl = (float)((ga[e >> 2] >> (8 * (e & 3))) & 255u) * frcp((float)((gb[e >> 2] >> (8 * (e & 3))) & 255u));
;             const float rh = (float)((ga[2 + (e >> 2)] >> (8 * (e & 3))) & 255u) * frcp((float)((gb[2 + (e >> 2)] >> (8 * (e & 3))) & 255u));
;             acc[ai][bj][e >> 2][nn][e & 3] *= rl;
;             acc[ai][bj][2 + (e >> 2)][nn][e & 3] *= rh;
;         }
;         __builtin_amdgcn_sched_barrier(0);
;     }
; }
	ds_read_b128 v[204:207], v157 offset:49152
	ds_read_b128 v[208:211], v157 offset:50176
	ds_read_b128 v[212:215], v156 offset:49152
	ds_read_b128 v[216:219], v156 offset:50176
	ds_read_b128 v[220:223], v155 offset:49152
	ds_read_b128 v[224:227], v155 offset:50176
	ds_read_b128 v[228:231], v154 offset:49152
	ds_read_b128 v[232:235], v154 offset:50176
	global_load_lds_dwordx4 v[172:173], off
	v_lshl_add_u64 v[172:173], s[20:21], 0, v[136:137]
	s_mov_b32 m0, s6
	s_nop 0
	global_load_lds_dwordx4 v[172:173], off
	s_barrier
	s_waitcnt lgkmcnt(0)
	s_setprio 1
	s_waitcnt lgkmcnt(0)
	v_mfma_f32_16x16x32_bf16 v[106:109], v[204:207], v[150:153], v[106:109]
	v_mfma_f32_16x16x32_bf16 v[122:125], v[204:207], v[196:199], v[122:125]
	v_mfma_f32_16x16x32_bf16 v[102:105], v[212:215], v[150:153], v[102:105]
	v_mfma_f32_16x16x32_bf16 v[118:121], v[212:215], v[196:199], v[118:121]
	v_mfma_f32_16x16x32_bf16 v[98:101], v[220:223], v[150:153], v[98:101]
	v_mfma_f32_16x16x32_bf16 v[114:117], v[220:223], v[196:199], v[114:117]
	v_mfma_f32_16x16x32_bf16 v[94:97], v[228:231], v[150:153], v[94:97]
	v_mfma_f32_16x16x32_bf16 v[110:113], v[228:231], v[196:199], v[110:113]
	v_mfma_f32_16x16x32_bf16 v[106:109], v[208:211], v[192:195], v[106:109]
	v_mfma_f32_16x16x32_bf16 v[122:125], v[208:211], v[200:203], v[122:125]
	v_mfma_f32_16x16x32_bf16 v[102:105], v[216:219], v[192:195], v[102:105]
	v_mfma_f32_16x16x32_bf16 v[118:121], v[216:219], v[200:203], v[118:121]
	v_mfma_f32_16x16x32_bf16 v[98:101], v[224:227], v[192:195], v[98:101]
	v_mfma_f32_16x16x32_bf16 v[114:117], v[224:227], v[200:203], v[114:117]
	v_mfma_f32_16x16x32_bf16 v[94:97], v[232:235], v[192:195], v[94:97]
	v_mfma_f32_16x16x32_bf16 v[110:113], v[232:235], v[200:203], v[110:113]
	s_setprio 0
	s_barrier
	s_add_u32 s16, s16, 0x20000
	s_addc_u32 s17, s17, 0
	v_readfirstlane_b32 s6, v186
	v_lshl_add_u64 v[150:151], s[16:17], 0, v[134:135]
	s_mov_b32 m0, s6
	v_readfirstlane_b32 s6, v187
	global_load_lds_dwordx4 v[150:151], off
	v_lshl_add_u64 v[150:151], s[16:17], 0, v[136:137]
	s_mov_b32 m0, s6
	s_nop 0
	global_load_lds_dwordx4 v[150:151], off
	s_waitcnt vmcnt(6)
	s_barrier
	s_setprio 1
	v_mfma_f32_16x16x32_bf16 v[126:129], v[204:207], v[236:239], v[126:129]
	v_mfma_f32_16x16x32_bf16 v[14:17], v[204:207], v[244:247], v[14:17]
	v_mfma_f32_16x16x32_bf16 v[34:37], v[212:215], v[236:239], v[34:37]
	v_mfma_f32_16x16x32_bf16 v[6:9], v[212:215], v[244:247], v[6:9]
	v_mfma_f32_16x16x32_bf16 v[38:41], v[220:223], v[236:239], v[38:41]
	v_mfma_f32_16x16x32_bf16 v[10:13], v[220:223], v[244:247], v[10:13]
	v_mfma_f32_16x16x32_bf16 v[22:25], v[228:231], v[236:239], v[22:25]
	v_mfma_f32_16x16x32_bf16 v[2:5], v[228:231], v[244:247], v[2:5]
	v_mfma_f32_16x16x32_bf16 v[126:129], v[208:211], v[240:243], v[126:129]
	v_mfma_f32_16x16x32_bf16 v[14:17], v[208:211], v[248:251], v[14:17]
	v_mfma_f32_16x16x32_bf16 v[34:37], v[216:219], v[240:243], v[34:37]
	v_mfma_f32_16x16x32_bf16 v[6:9], v[216:219], v[248:251], v[6:9]
	v_mfma_f32_16x16x32_bf16 v[38:41], v[224:227], v[240:243], v[38:41]
	v_mfma_f32_16x16x32_bf16 v[10:13], v[224:227], v[248:251], v[10:13]
	v_mfma_f32_16x16x32_bf16 v[22:25], v[232:235], v[240:243], v[22:25]
	v_mfma_f32_16x16x32_bf16 v[2:5], v[232:235], v[248:251], v[2:5]
	s_setprio 0
	s_addk_i32 s2, 0x80
	v_lshl_add_u64 v[130:131], v[130:131], 0, s[90:91]
	v_lshl_add_u64 v[132:133], v[132:133], 0, s[90:91]
	s_mov_b32 s6, s7
	s_barrier
	s_cbranch_vccnz .LBB0_56
	v_readlane_b32 s2, v255, 38
	s_add_u32 s26, s2, s12
	v_readlane_b32 s2, v255, 39
	s_addc_u32 s2, s2, s13
	v_readlane_b32 s6, v253, 42
	s_add_u32 s3, s6, s3
	v_readlane_b32 s6, v253, 43
	s_addc_u32 s34, s6, 0
	s_ashr_i32 s59, s58, 31
	s_lshl_b64 s[6:7], s[58:59], 16
	s_add_u32 s10, s6, 0x10000
	s_addc_u32 s11, s7, 0
	s_add_u32 s8, s74, s6
	v_mov_b32_e32 v130, v162
	s_addc_u32 s9, s75, s7
	s_add_u32 s56, s74, s10
	v_ashrrev_i32_e32 v131, 31, v130
	v_lshl_add_u64 v[130:131], v[130:131], 4, s[8:9]
	v_mov_b32_e32 v150, v162
	v_mov_b64_e32 v[242:243], v[130:131]
	s_addc_u32 s57, s75, s11
	v_ashrrev_i32_e32 v151, 31, v150
	v_lshl_add_u64 v[150:151], v[150:151], 4, s[56:57]
	v_mov_b64_e32 v[244:245], v[150:151]
	s_mov_b64 s[0:1], 0x2000
	global_load_dwordx4 v[210:213], v[242:243], off
	v_lshl_add_u64 v[242:243], v[242:243], 0, s[0:1]
	global_load_dwordx4 v[226:229], v[244:245], off
	v_lshl_add_u64 v[244:245], v[244:245], 0, s[0:1]
	global_load_dwordx4 v[214:217], v[242:243], off
	v_lshl_add_u64 v[242:243], v[242:243], 0, s[0:1]
	global_load_dwordx4 v[230:233], v[244:245], off
	v_lshl_add_u64 v[244:245], v[244:245], 0, s[0:1]
	global_load_dwordx4 v[218:221], v[242:243], off
	v_lshl_add_u64 v[242:243], v[242:243], 0, s[0:1]
	global_load_dwordx4 v[234:237], v[244:245], off
	v_lshl_add_u64 v[244:245], v[244:245], 0, s[0:1]
	global_load_dwordx4 v[222:225], v[242:243], off
	v_lshl_add_u64 v[242:243], v[242:243], 0, s[0:1]
	global_load_dwordx4 v[238:241], v[244:245], off
	v_lshl_add_u64 v[244:245], v[244:245], 0, s[0:1]
	s_waitcnt vmcnt(7)
	s_nop 1
	v_mov_b64_e32 v[130:131], v[210:211]
	v_mov_b64_e32 v[132:133], v[212:213]
	v_cvt_f32_ubyte3_e32 v199, v130
	v_cvt_f32_ubyte2_e32 v198, v130
	v_cvt_f32_ubyte1_e32 v201, v130
	v_cvt_f32_ubyte0_e32 v200, v130
	s_waitcnt vmcnt(6)
; DI float frcp(float x) { return __builtin_amdgcn_rcpf(x); }
; DI u32x4* gate_slot(const Params& P, int tile, int j, int g8) { return (u32x4*)slotp(P, SL_SK) + ((size_t)(tile * 3 + j) * 8 + g8) * 512 + tid(); }
; DI void merge_scale(const Params& P, int tile, int seg, f32x4 (&acc)[2][2][4][2]) {
; #pragma unroll
;     for (int g8 = 0; g8 < 8; ++g8) {
;         const int ai = g8 >> 2, bj = (g8 >> 1) & 1, nn = g8 & 1;
;         const u32x4 ga = *gate_slot(P, tile, seg, g8), gb = *gate_slot(P, tile, seg + 1, g8);
; #pragma unroll
;         for (int e = 0; e < 8; ++e) {
;             const float rl = (float)((ga[e >> 2] >> (8 * (e & 3))) & 255u) * frcp((float)((gb[e >> 2] >> (8 * (e & 3))) & 255u));
;             const float rh = (float)((ga[2 + (e >> 2)] >> (8 * (e & 3))) & 255u) * frcp((float)((gb[2 + (e >> 2)] >> (8 * (e & 3))) & 255u));
;             acc[ai][bj][e >> 2][nn][e & 3] *= rl;
;             acc[ai][bj][2 + (e >> 2)][nn][e & 3] *= rh;
;         }
;         __builtin_amdgcn_sched_barrier(0);
;     }
; }
	s_nop 1
	v_mov_b64_e32 v[192:193], v[226:227]
	v_mov_b64_e32 v[194:195], v[228:229]
	v_cvt_f32_ubyte0_e32 v151, v194
	v_cvt_f32_ubyte2_e32 v173, v194
	v_cvt_f32_ubyte0_e32 v150, v192
	v_rcp_iflag_f32_e32 v152, v151
	v_cvt_f32_ubyte1_e32 v151, v192
	v_cvt_f32_ubyte2_e32 v172, v192
	v_rcp_iflag_f32_e32 v196, v173
	v_cvt_f32_ubyte3_e32 v173, v192
	v_rcp_iflag_f32_e32 v150, v150
	v_rcp_iflag_f32_e32 v151, v151
	v_rcp_iflag_f32_e32 v172, v172
	v_rcp_iflag_f32_e32 v173, v173
	v_cvt_f32_ubyte1_e32 v153, v194
	v_cvt_f32_ubyte3_e32 v192, v194
	v_rcp_iflag_f32_e32 v153, v153
	v_rcp_iflag_f32_e32 v197, v192
	v_pk_mul_f32 v[150:151], v[150:151], v[200:201]
	v_pk_mul_f32 v[172:173], v[172:173], v[198:199]
	v_pk_mul_f32 v[18:19], v[18:19], v[150:151]
	v_pk_mul_f32 v[20:21], v[20:21], v[172:173]
	v_cvt_f32_ubyte3_e32 v151, v132
	v_cvt_f32_ubyte2_e32 v150, v132
	v_cvt_f32_ubyte1_e32 v173, v132
	v_cvt_f32_ubyte0_e32 v172, v132
	v_cvt_f32_ubyte0_e32 v130, v193
	v_pk_mul_f32 v[152:153], v[152:153], v[172:173]
	v_pk_mul_f32 v[150:151], v[196:197], v[150:151]
	v_rcp_iflag_f32_e32 v172, v130
	v_cvt_f32_ubyte0_e32 v130, v195
	v_pk_mul_f32 v[28:29], v[28:29], v[150:151]
	v_rcp_iflag_f32_e32 v150, v130
	v_cvt_f32_ubyte1_e32 v130, v193
	v_rcp_iflag_f32_e32 v173, v130
	v_cvt_f32_ubyte1_e32 v130, v195
	v_rcp_iflag_f32_e32 v151, v130
	v_cvt_f32_ubyte2_e32 v130, v193
	v_rcp_iflag_f32_e32 v192, v130
	v_cvt_f32_ubyte2_e32 v130, v195
	v_pk_mul_f32 v[26:27], v[26:27], v[152:153]
	v_rcp_iflag_f32_e32 v152, v130
	v_cvt_f32_ubyte3_e32 v130, v193
	v_rcp_iflag_f32_e32 v193, v130
	v_cvt_f32_ubyte3_e32 v130, v195
	v_rcp_iflag_f32_e32 v153, v130
	v_cvt_f32_ubyte3_e32 v195, v131
	v_cvt_f32_ubyte2_e32 v194, v131
	v_cvt_f32_ubyte1_e32 v197, v131
	v_cvt_f32_ubyte0_e32 v196, v131
	v_pk_mul_f32 v[130:131], v[172:173], v[196:197]
	v_pk_mul_f32 v[172:173], v[192:193], v[194:195]
	v_pk_mul_f32 v[30:31], v[30:31], v[130:131]
	v_pk_mul_f32 v[32:33], v[32:33], v[172:173]
	v_cvt_f32_ubyte3_e32 v131, v133
	v_cvt_f32_ubyte2_e32 v130, v133
	v_cvt_f32_ubyte1_e32 v173, v133
	v_cvt_f32_ubyte0_e32 v172, v133
	v_pk_mul_f32 v[132:133], v[150:151], v[172:173]
	v_pk_mul_f32 v[130:131], v[152:153], v[130:131]
	v_pk_mul_f32 v[42:43], v[42:43], v[132:133]
	v_pk_mul_f32 v[44:45], v[44:45], v[130:131]
	s_add_u32 s8, s62, s6
	v_mov_b32_e32 v130, v162
	s_addc_u32 s9, s63, s7
	s_mov_b32 s6, 0x13802000
	v_ashrrev_i32_e32 v131, 31, v130
	v_lshl_add_u64 v[130:131], v[130:131], 4, s[8:9]
	s_add_u32 s22, s62, s10
	v_add_co_u32_e32 v130, vcc, s6, v130
	s_addc_u32 s23, s63, s11
	s_nop 0
	v_addc_co_u32_e32 v131, vcc, 0, v131, vcc
	s_add_u32 s54, s22, 0x13802000
	v_mov_b32_e32 v150, v162
	s_addc_u32 s55, s23, 0
	v_ashrrev_i32_e32 v151, 31, v150
	v_lshl_add_u64 v[150:151], v[150:151], 4, s[54:55]
	s_waitcnt vmcnt(5)
	s_nop 1
	v_mov_b64_e32 v[130:131], v[214:215]
	v_mov_b64_e32 v[132:133], v[216:217]
	v_cvt_f32_ubyte3_e32 v199, v130
	v_cvt_f32_ubyte2_e32 v198, v130
	v_cvt_f32_ubyte1_e32 v201, v130
	v_cvt_f32_ubyte0_e32 v200, v130
	s_waitcnt vmcnt(4)
	s_nop 1
	v_mov_b64_e32 v[192:193], v[230:231]
	v_mov_b64_e32 v[194:195], v[232:233]
	v_cvt_f32_ubyte0_e32 v151, v194
	v_cvt_f32_ubyte2_e32 v173, v194
	v_cvt_f32_ubyte0_e32 v150, v192
	v_rcp_iflag_f32_e32 v152, v151
	v_cvt_f32_ubyte1_e32 v151, v192
	v_cvt_f32_ubyte2_e32 v172, v192
	v_rcp_iflag_f32_e32 v196, v173
	v_cvt_f32_ubyte3_e32 v173, v192
	v_rcp_iflag_f32_e32 v150, v150
	v_rcp_iflag_f32_e32 v151, v151
	v_rcp_iflag_f32_e32 v172, v172
	v_rcp_iflag_f32_e32 v173, v173
	v_cvt_f32_ubyte1_e32 v153, v194
	v_cvt_f32_ubyte3_e32 v192, v194
	v_rcp_iflag_f32_e32 v153, v153
	v_rcp_iflag_f32_e32 v197, v192
	v_pk_mul_f32 v[150:151], v[150:151], v[200:201]
	v_pk_mul_f32 v[172:173], v[172:173], v[198:199]
	v_pk_mul_f32 v[58:59], v[58:59], v[150:151]
	v_pk_mul_f32 v[60:61], v[60:61], v[172:173]
	v_cvt_f32_ubyte3_e32 v151, v132
	v_cvt_f32_ubyte2_e32 v150, v132
	v_cvt_f32_ubyte1_e32 v173, v132
	v_cvt_f32_ubyte0_e32 v172, v132
	v_cvt_f32_ubyte0_e32 v130, v193
	v_pk_mul_f32 v[152:153], v[152:153], v[172:173]
	v_pk_mul_f32 v[150:151], v[196:197], v[150:151]
	v_rcp_iflag_f32_e32 v172, v130
	v_cvt_f32_ubyte0_e32 v130, v195
	v_pk_mul_f32 v[52:53], v[52:53], v[150:151]
	v_rcp_iflag_f32_e32 v150, v130
	v_cvt_f32_ubyte1_e32 v130, v193
	v_rcp_iflag_f32_e32 v173, v130
	v_cvt_f32_ubyte1_e32 v130, v195
	v_rcp_iflag_f32_e32 v151, v130
	v_cvt_f32_ubyte2_e32 v130, v193
	v_rcp_iflag_f32_e32 v192, v130
	v_cvt_f32_ubyte2_e32 v130, v195
	v_pk_mul_f32 v[50:51], v[50:51], v[152:153]
	v_rcp_iflag_f32_e32 v152, v130
	v_cvt_f32_ubyte3_e32 v130, v193
	v_rcp_iflag_f32_e32 v193, v130
	v_cvt_f32_ubyte3_e32 v130, v195
	v_rcp_iflag_f32_e32 v153, v130
	v_cvt_f32_ubyte3_e32 v195, v131
	v_cvt_f32_ubyte2_e32 v194, v131
	v_cvt_f32_ubyte1_e32 v197, v131
	v_cvt_f32_ubyte0_e32 v196, v131
	v_pk_mul_f32 v[130:131], v[172:173], v[196:197]
	v_pk_mul_f32 v[172:173], v[192:193], v[194:195]
	v_pk_mul_f32 v[54:55], v[54:55], v[130:131]
	v_pk_mul_f32 v[56:57], v[56:57], v[172:173]
	v_cvt_f32_ubyte3_e32 v131, v133
	v_cvt_f32_ubyte2_e32 v130, v133
	v_cvt_f32_ubyte1_e32 v173, v133
	v_cvt_f32_ubyte0_e32 v172, v133
	v_pk_mul_f32 v[132:133], v[150:151], v[172:173]
	v_pk_mul_f32 v[130:131], v[152:153], v[130:131]
	v_pk_mul_f32 v[46:47], v[46:47], v[132:133]
	v_pk_mul_f32 v[48:49], v[48:49], v[130:131]
	v_mov_b32_e32 v130, v162
	s_mov_b32 s6, 0x13804000
	v_ashrrev_i32_e32 v131, 31, v130
	v_lshl_add_u64 v[130:131], v[130:131], 4, s[8:9]
	v_add_co_u32_e32 v130, vcc, s6, v130
	s_add_u32 s6, s22, 0x13804000
	s_nop 0
	v_addc_co_u32_e32 v131, vcc, 0, v131, vcc
	v_mov_b32_e32 v150, v162
	s_addc_u32 s7, s23, 0
	v_ashrrev_i32_e32 v151, 31, v150
	v_lshl_add_u64 v[150:151], v[150:151], 4, s[6:7]
	s_waitcnt vmcnt(3)
; DI float frcp(float x) { return __builtin_amdgcn_rcpf(x); }
; DI u32x4* gate_slot(const Params& P, int tile, int j, int g8) { return (u32x4*)slotp(P, SL_SK) + ((size_t)(tile * 3 + j) * 8 + g8) * 512 + tid(); }
; DI void merge_scale(const Params& P, int tile, int seg, f32x4 (&acc)[2][2][4][2]) {
; #pragma unroll
;     for (int g8 = 0; g8 < 8; ++g8) {
;         const int ai = g8 >> 2, bj = (g8 >> 1) & 1, nn = g8 & 1;
;         const u32x4 ga = *gate_slot(P, tile, seg, g8), gb = *gate_slot(P, tile, seg + 1, g8);
; #pragma unroll
;         for (int e = 0; e < 8; ++e) {
;             const float rl = (float)((ga[e >> 2] >> (8 * (e & 3))) & 255u) * frcp((float)((gb[e >> 2] >> (8 * (e & 3))) & 255u));
;             const float rh = (float)((ga[2 + (e >> 2)] >> (8 * (e & 3))) & 255u) * frcp((float)((gb[2 + (e >> 2)] >> (8 * (e & 3))) & 255u));
;             acc[ai][bj][e >> 2][nn][e & 3] *= rl;
;             acc[ai][bj][2 + (e >> 2)][nn][e & 3] *= rh;
;         }
;         __builtin_amdgcn_sched_barrier(0);
;     }
; }
	s_nop 1
	v_mov_b64_e32 v[130:131], v[218:219]
	v_mov_b64_e32 v[132:133], v[220:221]
	v_cvt_f32_ubyte3_e32 v199, v130
	v_cvt_f32_ubyte2_e32 v198, v130
	v_cvt_f32_ubyte1_e32 v201, v130
	v_cvt_f32_ubyte0_e32 v200, v130
	s_waitcnt vmcnt(2)
	s_nop 1
	v_mov_b64_e32 v[192:193], v[234:235]
	v_mov_b64_e32 v[194:195], v[236:237]
	v_cvt_f32_ubyte0_e32 v151, v194
	v_cvt_f32_ubyte2_e32 v173, v194
	v_cvt_f32_ubyte0_e32 v150, v192
	v_rcp_iflag_f32_e32 v152, v151
	v_cvt_f32_ubyte1_e32 v151, v192
	v_cvt_f32_ubyte2_e32 v172, v192
	v_rcp_iflag_f32_e32 v196, v173
	v_cvt_f32_ubyte3_e32 v173, v192
	v_rcp_iflag_f32_e32 v150, v150
	v_rcp_iflag_f32_e32 v151, v151
	v_rcp_iflag_f32_e32 v172, v172
	v_rcp_iflag_f32_e32 v173, v173
	v_cvt_f32_ubyte1_e32 v153, v194
	v_cvt_f32_ubyte3_e32 v192, v194
	v_rcp_iflag_f32_e32 v153, v153
	v_rcp_iflag_f32_e32 v197, v192
	v_pk_mul_f32 v[150:151], v[150:151], v[200:201]
	v_pk_mul_f32 v[172:173], v[172:173], v[198:199]
	v_pk_mul_f32 v[74:75], v[74:75], v[150:151]
	v_pk_mul_f32 v[76:77], v[76:77], v[172:173]
	v_cvt_f32_ubyte3_e32 v151, v132
	v_cvt_f32_ubyte2_e32 v150, v132
	v_cvt_f32_ubyte1_e32 v173, v132
	v_cvt_f32_ubyte0_e32 v172, v132
	v_cvt_f32_ubyte0_e32 v130, v193
	v_pk_mul_f32 v[152:153], v[152:153], v[172:173]
	v_pk_mul_f32 v[150:151], v[196:197], v[150:151]
	v_rcp_iflag_f32_e32 v172, v130
	v_cvt_f32_ubyte0_e32 v130, v195
	v_pk_mul_f32 v[68:69], v[68:69], v[150:151]
	v_rcp_iflag_f32_e32 v150, v130
	v_cvt_f32_ubyte1_e32 v130, v193
	v_rcp_iflag_f32_e32 v173, v130
	v_cvt_f32_ubyte1_e32 v130, v195
	v_rcp_iflag_f32_e32 v151, v130
	v_cvt_f32_ubyte2_e32 v130, v193
	v_rcp_iflag_f32_e32 v192, v130
	v_cvt_f32_ubyte2_e32 v130, v195
	v_pk_mul_f32 v[66:67], v[66:67], v[152:153]
	v_rcp_iflag_f32_e32 v152, v130
	v_cvt_f32_ubyte3_e32 v130, v193
	v_rcp_iflag_f32_e32 v193, v130
	v_cvt_f32_ubyte3_e32 v130, v195
	v_rcp_iflag_f32_e32 v153, v130
	v_cvt_f32_ubyte3_e32 v195, v131
	v_cvt_f32_ubyte2_e32 v194, v131
	v_cvt_f32_ubyte1_e32 v197, v131
	v_cvt_f32_ubyte0_e32 v196, v131
	v_pk_mul_f32 v[130:131], v[172:173], v[196:197]
	v_pk_mul_f32 v[172:173], v[192:193], v[194:195]
	v_pk_mul_f32 v[70:71], v[70:71], v[130:131]
	v_pk_mul_f32 v[72:73], v[72:73], v[172:173]
	v_cvt_f32_ubyte3_e32 v131, v133
	v_cvt_f32_ubyte2_e32 v130, v133
	v_cvt_f32_ubyte1_e32 v173, v133
	v_cvt_f32_ubyte0_e32 v172, v133
	v_pk_mul_f32 v[132:133], v[150:151], v[172:173]
	v_pk_mul_f32 v[130:131], v[152:153], v[130:131]
	v_pk_mul_f32 v[62:63], v[62:63], v[132:133]
	v_pk_mul_f32 v[64:65], v[64:65], v[130:131]
	v_mov_b32_e32 v130, v162
	s_mov_b32 s10, 0x13806000
	v_ashrrev_i32_e32 v131, 31, v130
	v_lshl_add_u64 v[130:131], v[130:131], 4, s[8:9]
	v_add_co_u32_e32 v130, vcc, s10, v130
	s_add_u32 s10, s22, 0x13806000
	s_nop 0
	v_addc_co_u32_e32 v131, vcc, 0, v131, vcc
	v_mov_b32_e32 v150, v162
	s_addc_u32 s11, s23, 0
	v_ashrrev_i32_e32 v151, 31, v150
	v_lshl_add_u64 v[150:151], v[150:151], 4, s[10:11]
	s_waitcnt vmcnt(1)
	s_nop 1
	v_mov_b64_e32 v[130:131], v[222:223]
	v_mov_b64_e32 v[132:133], v[224:225]
	v_cvt_f32_ubyte3_e32 v199, v130
	v_cvt_f32_ubyte2_e32 v198, v130
	v_cvt_f32_ubyte1_e32 v201, v130
	v_cvt_f32_ubyte0_e32 v200, v130
	s_waitcnt vmcnt(0)
	s_nop 1
	v_mov_b64_e32 v[192:193], v[238:239]
	v_mov_b64_e32 v[194:195], v[240:241]
	global_load_dwordx4 v[210:213], v[242:243], off
	v_lshl_add_u64 v[242:243], v[242:243], 0, s[0:1]
	global_load_dwordx4 v[226:229], v[244:245], off
	v_lshl_add_u64 v[244:245], v[244:245], 0, s[0:1]
	global_load_dwordx4 v[214:217], v[242:243], off
	v_lshl_add_u64 v[242:243], v[242:243], 0, s[0:1]
	global_load_dwordx4 v[230:233], v[244:245], off
	v_lshl_add_u64 v[244:245], v[244:245], 0, s[0:1]
	global_load_dwordx4 v[218:221], v[242:243], off
	v_lshl_add_u64 v[242:243], v[242:243], 0, s[0:1]
	global_load_dwordx4 v[234:237], v[244:245], off
	v_lshl_add_u64 v[244:245], v[244:245], 0, s[0:1]
	global_load_dwordx4 v[222:225], v[242:243], off
	v_lshl_add_u64 v[242:243], v[242:243], 0, s[0:1]
	global_load_dwordx4 v[238:241], v[244:245], off
	v_lshl_add_u64 v[244:245], v[244:245], 0, s[0:1]
	v_cvt_f32_ubyte0_e32 v151, v194
	v_cvt_f32_ubyte2_e32 v173, v194
	v_cvt_f32_ubyte0_e32 v150, v192
	v_rcp_iflag_f32_e32 v152, v151
	v_cvt_f32_ubyte1_e32 v151, v192
	v_cvt_f32_ubyte2_e32 v172, v192
	v_rcp_iflag_f32_e32 v196, v173
	v_cvt_f32_ubyte3_e32 v173, v192
	v_rcp_iflag_f32_e32 v150, v150
	v_rcp_iflag_f32_e32 v151, v151
	v_rcp_iflag_f32_e32 v172, v172
	v_rcp_iflag_f32_e32 v173, v173
	v_cvt_f32_ubyte1_e32 v153, v194
	v_cvt_f32_ubyte3_e32 v192, v194
	v_rcp_iflag_f32_e32 v153, v153
	v_rcp_iflag_f32_e32 v197, v192
	v_pk_mul_f32 v[150:151], v[150:151], v[200:201]
	v_pk_mul_f32 v[172:173], v[172:173], v[198:199]
	v_pk_mul_f32 v[90:91], v[90:91], v[150:151]
	v_pk_mul_f32 v[92:93], v[92:93], v[172:173]
	v_cvt_f32_ubyte3_e32 v151, v132
	v_cvt_f32_ubyte2_e32 v150, v132
	v_cvt_f32_ubyte1_e32 v173, v132
	v_cvt_f32_ubyte0_e32 v172, v132
	v_cvt_f32_ubyte0_e32 v130, v193
	v_pk_mul_f32 v[152:153], v[152:153], v[172:173]
	v_pk_mul_f32 v[150:151], v[196:197], v[150:151]
	v_rcp_iflag_f32_e32 v172, v130
	v_cvt_f32_ubyte0_e32 v130, v195
	v_pk_mul_f32 v[84:85], v[84:85], v[150:151]
	v_rcp_iflag_f32_e32 v150, v130
	v_cvt_f32_ubyte1_e32 v130, v193
	v_rcp_iflag_f32_e32 v173, v130
	v_cvt_f32_ubyte1_e32 v130, v195
	v_rcp_iflag_f32_e32 v151, v130
	v_cvt_f32_ubyte2_e32 v130, v193
	v_rcp_iflag_f32_e32 v192, v130
	v_cvt_f32_ubyte2_e32 v130, v195
	v_pk_mul_f32 v[82:83], v[82:83], v[152:153]
	v_rcp_iflag_f32_e32 v152, v130
	v_cvt_f32_ubyte3_e32 v130, v193
	v_rcp_iflag_f32_e32 v193, v130
	v_cvt_f32_ubyte3_e32 v130, v195
	v_rcp_iflag_f32_e32 v153, v130
	v_cvt_f32_ubyte3_e32 v195, v131
	v_cvt_f32_ubyte2_e32 v194, v131
	v_cvt_f32_ubyte1_e32 v197, v131
	v_cvt_f32_ubyte0_e32 v196, v131
	v_pk_mul_f32 v[130:131], v[172:173], v[196:197]
	v_pk_mul_f32 v[172:173], v[192:193], v[194:195]
	v_pk_mul_f32 v[86:87], v[86:87], v[130:131]
	v_pk_mul_f32 v[88:89], v[88:89], v[172:173]
	v_cvt_f32_ubyte3_e32 v131, v133
	v_cvt_f32_ubyte2_e32 v130, v133
	v_cvt_f32_ubyte1_e32 v173, v133
	v_cvt_f32_ubyte0_e32 v172, v133
	v_pk_mul_f32 v[132:133], v[150:151], v[172:173]
	v_pk_mul_f32 v[130:131], v[152:153], v[130:131]
	v_pk_mul_f32 v[78:79], v[78:79], v[132:133]
	v_pk_mul_f32 v[80:81], v[80:81], v[130:131]
	v_mov_b32_e32 v130, v162
	s_mov_b32 s12, 0x13808000
	v_ashrrev_i32_e32 v131, 31, v130
	v_lshl_add_u64 v[130:131], v[130:131], 4, s[8:9]
	v_add_co_u32_e32 v130, vcc, s12, v130
	s_add_u32 s12, s22, 0x13808000
	s_nop 0
	v_addc_co_u32_e32 v131, vcc, 0, v131, vcc
	v_mov_b32_e32 v150, v162
	s_addc_u32 s13, s23, 0
	v_ashrrev_i32_e32 v151, 31, v150
	v_lshl_add_u64 v[150:151], v[150:151], 4, s[12:13]
	s_waitcnt vmcnt(7)
; DI float frcp(float x) { return __builtin_amdgcn_rcpf(x); }
; DI u32x4* gate_slot(const Params& P, int tile, int j, int g8) { return (u32x4*)slotp(P, SL_SK) + ((size_t)(tile * 3 + j) * 8 + g8) * 512 + tid(); }
; DI void merge_scale(const Params& P, int tile, int seg, f32x4 (&acc)[2][2][4][2]) {
; #pragma unroll
;     for (int g8 = 0; g8 < 8; ++g8) {
;         const int ai = g8 >> 2, bj = (g8 >> 1) & 1, nn = g8 & 1;
;         const u32x4 ga = *gate_slot(P, tile, seg, g8), gb = *gate_slot(P, tile, seg + 1, g8);
; #pragma unroll
;         for (int e = 0; e < 8; ++e) {
;             const float rl = (float)((ga[e >> 2] >> (8 * (e & 3))) & 255u) * frcp((float)((gb[e >> 2] >> (8 * (e & 3))) & 255u));
;             const float rh = (float)((ga[2 + (e >> 2)] >> (8 * (e & 3))) & 255u) * frcp((float)((gb[2 + (e >> 2)] >> (8 * (e & 3))) & 255u));
;             acc[ai][bj][e >> 2][nn][e & 3] *= rl;
;             acc[ai][bj][2 + (e >> 2)][nn][e & 3] *= rh;
;         }
;         __builtin_amdgcn_sched_barrier(0);
;     }
; }
	s_nop 1
	v_mov_b64_e32 v[130:131], v[210:211]
	v_mov_b64_e32 v[132:133], v[212:213]
	v_cvt_f32_ubyte3_e32 v199, v130
	v_cvt_f32_ubyte2_e32 v198, v130
	v_cvt_f32_ubyte1_e32 v201, v130
	v_cvt_f32_ubyte0_e32 v200, v130
	s_waitcnt vmcnt(6)
	s_nop 1
	v_mov_b64_e32 v[192:193], v[226:227]
	v_mov_b64_e32 v[194:195], v[228:229]
	v_cvt_f32_ubyte0_e32 v151, v194
	v_cvt_f32_ubyte2_e32 v173, v194
	v_cvt_f32_ubyte0_e32 v150, v192
	v_rcp_iflag_f32_e32 v152, v151
	v_cvt_f32_ubyte1_e32 v151, v192
	v_cvt_f32_ubyte2_e32 v172, v192
	v_rcp_iflag_f32_e32 v196, v173
	v_cvt_f32_ubyte3_e32 v173, v192
	v_rcp_iflag_f32_e32 v150, v150
	v_rcp_iflag_f32_e32 v151, v151
	v_rcp_iflag_f32_e32 v172, v172
	v_rcp_iflag_f32_e32 v173, v173
	v_cvt_f32_ubyte1_e32 v153, v194
	v_cvt_f32_ubyte3_e32 v192, v194
	v_rcp_iflag_f32_e32 v153, v153
	v_rcp_iflag_f32_e32 v197, v192
	v_pk_mul_f32 v[150:151], v[150:151], v[200:201]
	v_pk_mul_f32 v[172:173], v[172:173], v[198:199]
	v_pk_mul_f32 v[106:107], v[106:107], v[150:151]
	v_pk_mul_f32 v[108:109], v[108:109], v[172:173]
	v_cvt_f32_ubyte3_e32 v151, v132
	v_cvt_f32_ubyte2_e32 v150, v132
	v_cvt_f32_ubyte1_e32 v173, v132
	v_cvt_f32_ubyte0_e32 v172, v132
	v_cvt_f32_ubyte0_e32 v130, v193
	v_pk_mul_f32 v[152:153], v[152:153], v[172:173]
	v_pk_mul_f32 v[150:151], v[196:197], v[150:151]
	v_rcp_iflag_f32_e32 v172, v130
	v_cvt_f32_ubyte0_e32 v130, v195
	v_pk_mul_f32 v[100:101], v[100:101], v[150:151]
	v_rcp_iflag_f32_e32 v150, v130
	v_cvt_f32_ubyte1_e32 v130, v193
	v_rcp_iflag_f32_e32 v173, v130
	v_cvt_f32_ubyte1_e32 v130, v195
	v_rcp_iflag_f32_e32 v151, v130
	v_cvt_f32_ubyte2_e32 v130, v193
	v_rcp_iflag_f32_e32 v192, v130
	v_cvt_f32_ubyte2_e32 v130, v195
	v_pk_mul_f32 v[98:99], v[98:99], v[152:153]
	v_rcp_iflag_f32_e32 v152, v130
	v_cvt_f32_ubyte3_e32 v130, v193
	v_rcp_iflag_f32_e32 v193, v130
	v_cvt_f32_ubyte3_e32 v130, v195
	v_rcp_iflag_f32_e32 v153, v130
	v_cvt_f32_ubyte3_e32 v195, v131
	v_cvt_f32_ubyte2_e32 v194, v131
	v_cvt_f32_ubyte1_e32 v197, v131
	v_cvt_f32_ubyte0_e32 v196, v131
	v_pk_mul_f32 v[130:131], v[172:173], v[196:197]
	v_pk_mul_f32 v[172:173], v[192:193], v[194:195]
	v_pk_mul_f32 v[102:103], v[102:103], v[130:131]
	v_pk_mul_f32 v[104:105], v[104:105], v[172:173]
	v_cvt_f32_ubyte3_e32 v131, v133
	v_cvt_f32_ubyte2_e32 v130, v133
	v_cvt_f32_ubyte1_e32 v173, v133
	v_cvt_f32_ubyte0_e32 v172, v133
	v_pk_mul_f32 v[132:133], v[150:151], v[172:173]
	v_pk_mul_f32 v[130:131], v[152:153], v[130:131]
	v_pk_mul_f32 v[94:95], v[94:95], v[132:133]
	v_pk_mul_f32 v[96:97], v[96:97], v[130:131]
	v_mov_b32_e32 v130, v162
	s_mov_b32 s16, 0x1380a000
	v_ashrrev_i32_e32 v131, 31, v130
	v_lshl_add_u64 v[130:131], v[130:131], 4, s[8:9]
	v_add_co_u32_e32 v130, vcc, s16, v130
	s_add_u32 s16, s22, 0x1380a000
	s_nop 0
	v_addc_co_u32_e32 v131, vcc, 0, v131, vcc
	v_mov_b32_e32 v150, v162
	s_addc_u32 s17, s23, 0
	v_ashrrev_i32_e32 v151, 31, v150
	v_lshl_add_u64 v[150:151], v[150:151], 4, s[16:17]
	s_waitcnt vmcnt(5)
	s_nop 1
	v_mov_b64_e32 v[130:131], v[214:215]
	v_mov_b64_e32 v[132:133], v[216:217]
	v_cvt_f32_ubyte3_e32 v199, v130
	v_cvt_f32_ubyte2_e32 v198, v130
	v_cvt_f32_ubyte1_e32 v201, v130
	v_cvt_f32_ubyte0_e32 v200, v130
	s_waitcnt vmcnt(4)
	s_nop 1
	v_mov_b64_e32 v[192:193], v[230:231]
	v_mov_b64_e32 v[194:195], v[232:233]
	v_cvt_f32_ubyte0_e32 v151, v194
	v_cvt_f32_ubyte2_e32 v173, v194
	v_cvt_f32_ubyte0_e32 v150, v192
	v_rcp_iflag_f32_e32 v152, v151
	v_cvt_f32_ubyte1_e32 v151, v192
	v_cvt_f32_ubyte2_e32 v172, v192
	v_rcp_iflag_f32_e32 v196, v173
	v_cvt_f32_ubyte3_e32 v173, v192
	v_rcp_iflag_f32_e32 v150, v150
	v_rcp_iflag_f32_e32 v151, v151
	v_rcp_iflag_f32_e32 v172, v172
	v_rcp_iflag_f32_e32 v173, v173
	v_cvt_f32_ubyte1_e32 v153, v194
	v_cvt_f32_ubyte3_e32 v192, v194
	v_rcp_iflag_f32_e32 v153, v153
	v_rcp_iflag_f32_e32 v197, v192
	v_pk_mul_f32 v[150:151], v[150:151], v[200:201]
	v_pk_mul_f32 v[172:173], v[172:173], v[198:199]
	v_pk_mul_f32 v[122:123], v[122:123], v[150:151]
	v_pk_mul_f32 v[124:125], v[124:125], v[172:173]
	v_cvt_f32_ubyte3_e32 v151, v132
	v_cvt_f32_ubyte2_e32 v150, v132
	v_cvt_f32_ubyte1_e32 v173, v132
	v_cvt_f32_ubyte0_e32 v172, v132
	v_cvt_f32_ubyte0_e32 v130, v193
	v_pk_mul_f32 v[152:153], v[152:153], v[172:173]
	v_pk_mul_f32 v[150:151], v[196:197], v[150:151]
	v_rcp_iflag_f32_e32 v172, v130
	v_cvt_f32_ubyte0_e32 v130, v195
	v_pk_mul_f32 v[116:117], v[116:117], v[150:151]
	v_rcp_iflag_f32_e32 v150, v130
	v_cvt_f32_ubyte1_e32 v130, v193
	v_rcp_iflag_f32_e32 v173, v130
	v_cvt_f32_ubyte1_e32 v130, v195
	v_rcp_iflag_f32_e32 v151, v130
	v_cvt_f32_ubyte2_e32 v130, v193
	v_rcp_iflag_f32_e32 v192, v130
	v_cvt_f32_ubyte2_e32 v130, v195
	v_pk_mul_f32 v[114:115], v[114:115], v[152:153]
	v_rcp_iflag_f32_e32 v152, v130
	v_cvt_f32_ubyte3_e32 v130, v193
	v_rcp_iflag_f32_e32 v193, v130
	v_cvt_f32_ubyte3_e32 v130, v195
	v_rcp_iflag_f32_e32 v153, v130
	v_cvt_f32_ubyte3_e32 v195, v131
	v_cvt_f32_ubyte2_e32 v194, v131
	v_cvt_f32_ubyte1_e32 v197, v131
	v_cvt_f32_ubyte0_e32 v196, v131
	v_pk_mul_f32 v[130:131], v[172:173], v[196:197]
	v_pk_mul_f32 v[172:173], v[192:193], v[194:195]
	v_pk_mul_f32 v[118:119], v[118:119], v[130:131]
	v_pk_mul_f32 v[120:121], v[120:121], v[172:173]
	v_cvt_f32_ubyte3_e32 v131, v133
	v_cvt_f32_ubyte2_e32 v130, v133
	v_cvt_f32_ubyte1_e32 v173, v133
	v_cvt_f32_ubyte0_e32 v172, v133
	v_pk_mul_f32 v[132:133], v[150:151], v[172:173]
	v_pk_mul_f32 v[130:131], v[152:153], v[130:131]
	v_pk_mul_f32 v[110:111], v[110:111], v[132:133]
	v_pk_mul_f32 v[112:113], v[112:113], v[130:131]
	v_mov_b32_e32 v130, v162
	s_mov_b32 s20, 0x1380c000
	v_ashrrev_i32_e32 v131, 31, v130
	v_lshl_add_u64 v[130:131], v[130:131], 4, s[8:9]
	v_add_co_u32_e32 v130, vcc, s20, v130
	s_add_u32 s20, s22, 0x1380c000
	s_nop 0
	v_addc_co_u32_e32 v131, vcc, 0, v131, vcc
	v_mov_b32_e32 v150, v162
	s_addc_u32 s21, s23, 0
	v_ashrrev_i32_e32 v151, 31, v150
	v_lshl_add_u64 v[150:151], v[150:151], 4, s[20:21]
	s_waitcnt vmcnt(3)
; DI float frcp(float x) { return __builtin_amdgcn_rcpf(x); }
; DI u32x4* gate_slot(const Params& P, int tile, int j, int g8) { return (u32x4*)slotp(P, SL_SK) + ((size_t)(tile * 3 + j) * 8 + g8) * 512 + tid(); }
; DI void merge_scale(const Params& P, int tile, int seg, f32x4 (&acc)[2][2][4][2]) {
; #pragma unroll
;     for (int g8 = 0; g8 < 8; ++g8) {
;         const int ai = g8 >> 2, bj = (g8 >> 1) & 1, nn = g8 & 1;
;         const u32x4 ga = *gate_slot(P, tile, seg, g8), gb = *gate_slot(P, tile, seg + 1, g8);
; #pragma unroll
;         for (int e = 0; e < 8; ++e) {
;             const float rl = (float)((ga[e >> 2] >> (8 * (e & 3))) & 255u) * frcp((float)((gb[e >> 2] >> (8 * (e & 3))) & 255u));
;             const float rh = (float)((ga[2 + (e >> 2)] >> (8 * (e & 3))) & 255u) * frcp((float)((gb[2 + (e >> 2)] >> (8 * (e & 3))) & 255u));
;             acc[ai][bj][e >> 2][nn][e & 3] *= rl;
;             acc[ai][bj][2 + (e >> 2)][nn][e & 3] *= rh;
;         }
;         __builtin_amdgcn_sched_barrier(0);
;     }
; }
	s_nop 1
	v_mov_b64_e32 v[130:131], v[218:219]
	v_mov_b64_e32 v[132:133], v[220:221]
	v_cvt_f32_ubyte3_e32 v199, v130
	v_cvt_f32_ubyte2_e32 v198, v130
	v_cvt_f32_ubyte1_e32 v201, v130
	v_cvt_f32_ubyte0_e32 v200, v130
	s_waitcnt vmcnt(2)
	s_nop 1
	v_mov_b64_e32 v[192:193], v[234:235]
	v_mov_b64_e32 v[194:195], v[236:237]
	v_cvt_f32_ubyte0_e32 v151, v194
	v_cvt_f32_ubyte2_e32 v173, v194
	v_cvt_f32_ubyte0_e32 v150, v192
	v_rcp_iflag_f32_e32 v152, v151
	v_cvt_f32_ubyte1_e32 v151, v192
	v_cvt_f32_ubyte2_e32 v172, v192
	v_rcp_iflag_f32_e32 v196, v173
	v_cvt_f32_ubyte3_e32 v173, v192
	v_rcp_iflag_f32_e32 v150, v150
	v_rcp_iflag_f32_e32 v151, v151
	v_rcp_iflag_f32_e32 v172, v172
	v_rcp_iflag_f32_e32 v173, v173
	v_cvt_f32_ubyte1_e32 v153, v194
	v_cvt_f32_ubyte3_e32 v192, v194
	v_rcp_iflag_f32_e32 v153, v153
	v_rcp_iflag_f32_e32 v197, v192
	v_pk_mul_f32 v[150:151], v[150:151], v[200:201]
	v_pk_mul_f32 v[172:173], v[172:173], v[198:199]
	v_pk_mul_f32 v[126:127], v[126:127], v[150:151]
	v_pk_mul_f32 v[128:129], v[128:129], v[172:173]
	v_cvt_f32_ubyte3_e32 v151, v132
	v_cvt_f32_ubyte2_e32 v150, v132
	v_cvt_f32_ubyte1_e32 v173, v132
	v_cvt_f32_ubyte0_e32 v172, v132
	v_cvt_f32_ubyte0_e32 v130, v193
	v_pk_mul_f32 v[152:153], v[152:153], v[172:173]
	v_pk_mul_f32 v[150:151], v[196:197], v[150:151]
	v_rcp_iflag_f32_e32 v172, v130
	v_cvt_f32_ubyte0_e32 v130, v195
	v_pk_mul_f32 v[40:41], v[40:41], v[150:151]
	v_rcp_iflag_f32_e32 v150, v130
	v_cvt_f32_ubyte1_e32 v130, v193
	v_rcp_iflag_f32_e32 v173, v130
	v_cvt_f32_ubyte1_e32 v130, v195
	v_rcp_iflag_f32_e32 v151, v130
	v_cvt_f32_ubyte2_e32 v130, v193
	v_rcp_iflag_f32_e32 v192, v130
	v_cvt_f32_ubyte2_e32 v130, v195
	v_pk_mul_f32 v[38:39], v[38:39], v[152:153]
	v_rcp_iflag_f32_e32 v152, v130
	v_cvt_f32_ubyte3_e32 v130, v193
	v_rcp_iflag_f32_e32 v193, v130
	v_cvt_f32_ubyte3_e32 v130, v195
	v_rcp_iflag_f32_e32 v153, v130
	v_cvt_f32_ubyte3_e32 v195, v131
	v_cvt_f32_ubyte2_e32 v194, v131
	v_cvt_f32_ubyte1_e32 v197, v131
	v_cvt_f32_ubyte0_e32 v196, v131
	v_pk_mul_f32 v[130:131], v[172:173], v[196:197]
	v_pk_mul_f32 v[172:173], v[192:193], v[194:195]
	v_pk_mul_f32 v[34:35], v[34:35], v[130:131]
	v_pk_mul_f32 v[36:37], v[36:37], v[172:173]
	v_cvt_f32_ubyte3_e32 v131, v133
	v_cvt_f32_ubyte2_e32 v130, v133
	v_cvt_f32_ubyte1_e32 v173, v133
	v_cvt_f32_ubyte0_e32 v172, v133
	v_pk_mul_f32 v[132:133], v[150:151], v[172:173]
	v_pk_mul_f32 v[130:131], v[152:153], v[130:131]
	v_pk_mul_f32 v[22:23], v[22:23], v[132:133]
	v_pk_mul_f32 v[24:25], v[24:25], v[130:131]
	v_mov_b32_e32 v130, v162
	s_add_u32 s22, s22, 0x1380e000
	v_ashrrev_i32_e32 v131, 31, v130
	v_lshl_add_u64 v[130:131], v[130:131], 4, s[8:9]
	s_mov_b32 s8, 0x1380e000
	v_add_co_u32_e32 v130, vcc, s8, v130
	v_mov_b32_e32 v150, v162
	s_nop 0
	v_addc_co_u32_e32 v131, vcc, 0, v131, vcc
	s_addc_u32 s23, s23, 0
	v_ashrrev_i32_e32 v151, 31, v150
	v_lshl_add_u64 v[150:151], v[150:151], 4, s[22:23]
	s_waitcnt vmcnt(1)
	s_nop 1
	v_mov_b64_e32 v[130:131], v[222:223]
	v_mov_b64_e32 v[132:133], v[224:225]
	v_cvt_f32_ubyte3_e32 v199, v130
	v_cvt_f32_ubyte2_e32 v198, v130
	v_cvt_f32_ubyte1_e32 v201, v130
	v_cvt_f32_ubyte0_e32 v200, v130
	s_waitcnt vmcnt(0)
	s_nop 1
	v_mov_b64_e32 v[192:193], v[238:239]
	v_mov_b64_e32 v[194:195], v[240:241]
	v_cvt_f32_ubyte0_e32 v151, v194
	v_cvt_f32_ubyte2_e32 v173, v194
	v_cvt_f32_ubyte0_e32 v150, v192
	v_rcp_iflag_f32_e32 v152, v151
	v_cvt_f32_ubyte1_e32 v151, v192
	v_cvt_f32_ubyte2_e32 v172, v192
	v_rcp_iflag_f32_e32 v196, v173
	v_cvt_f32_ubyte3_e32 v173, v192
	v_rcp_iflag_f32_e32 v150, v150
	v_rcp_iflag_f32_e32 v151, v151
	v_rcp_iflag_f32_e32 v172, v172
	v_rcp_iflag_f32_e32 v173, v173
	v_cvt_f32_ubyte1_e32 v153, v194
	v_cvt_f32_ubyte3_e32 v192, v194
	v_rcp_iflag_f32_e32 v153, v153
	v_rcp_iflag_f32_e32 v197, v192
	v_pk_mul_f32 v[150:151], v[150:151], v[200:201]
	v_pk_mul_f32 v[172:173], v[172:173], v[198:199]
	v_pk_mul_f32 v[14:15], v[14:15], v[150:151]
	v_pk_mul_f32 v[16:17], v[16:17], v[172:173]
	v_cvt_f32_ubyte3_e32 v151, v132
	v_cvt_f32_ubyte2_e32 v150, v132
	v_cvt_f32_ubyte1_e32 v173, v132
	v_cvt_f32_ubyte0_e32 v172, v132
	v_cvt_f32_ubyte0_e32 v130, v193
	v_pk_mul_f32 v[152:153], v[152:153], v[172:173]
	v_pk_mul_f32 v[150:151], v[196:197], v[150:151]
	v_rcp_iflag_f32_e32 v172, v130
	v_cvt_f32_ubyte0_e32 v130, v195
	v_pk_mul_f32 v[12:13], v[12:13], v[150:151]
	v_rcp_iflag_f32_e32 v150, v130
	v_cvt_f32_ubyte1_e32 v130, v193
	v_rcp_iflag_f32_e32 v173, v130
	v_cvt_f32_ubyte1_e32 v130, v195
	v_rcp_iflag_f32_e32 v151, v130
	v_cvt_f32_ubyte2_e32 v130, v193
	v_rcp_iflag_f32_e32 v192, v130
	v_cvt_f32_ubyte2_e32 v130, v195
	v_pk_mul_f32 v[10:11], v[10:11], v[152:153]
	v_rcp_iflag_f32_e32 v152, v130
	v_cvt_f32_ubyte3_e32 v130, v193
	v_rcp_iflag_f32_e32 v193, v130
	v_cvt_f32_ubyte3_e32 v130, v195
	v_rcp_iflag_f32_e32 v153, v130
	v_cvt_f32_ubyte3_e32 v195, v131
	v_cvt_f32_ubyte2_e32 v194, v131
	v_cvt_f32_ubyte1_e32 v197, v131
	v_cvt_f32_ubyte0_e32 v196, v131
	v_pk_mul_f32 v[130:131], v[172:173], v[196:197]
	v_pk_mul_f32 v[172:173], v[192:193], v[194:195]
	v_pk_mul_f32 v[6:7], v[6:7], v[130:131]
	v_pk_mul_f32 v[8:9], v[8:9], v[172:173]
	v_cvt_f32_ubyte3_e32 v131, v133
	v_cvt_f32_ubyte2_e32 v130, v133
	v_cvt_f32_ubyte1_e32 v173, v133
	v_cvt_f32_ubyte0_e32 v172, v133
	v_pk_mul_f32 v[132:133], v[150:151], v[172:173]
	v_pk_mul_f32 v[130:131], v[152:153], v[130:131]
	v_pk_mul_f32 v[2:3], v[2:3], v[132:133]
	v_pk_mul_f32 v[4:5], v[4:5], v[130:131]
	s_mov_b64 s[8:9], s[50:51]
	v_lshl_add_u64 v[130:131], s[8:9], 0, v[146:147]
	v_lshl_add_u64 v[132:133], s[8:9], 0, v[148:149]
	s_mov_b32 s8, 6
	s_movk_i32 s9, 0x2c0
; #define STAGE(P, BASE, br, kt) do { const bf16_t* g_ = (BASE) + (size_t)(br) * K + (size_t)(kt) * 64; \
;         _Pragma("unroll") for (int i_ = 0; i_ < 2; ++i_) \
;             __builtin_amdgcn_global_load_lds((const unsigned*)(g_ + gofs[i_]), (lds_ptr_t)((P) + wb + i_ * 8192), 16, 0, 0); } while (0)
; #define LDA(dst, b, hh) _Pragma("unroll") for (int m = 0; m < 4; ++m) _Pragma("unroll") for (int k = 0; k < 2; ++k) \
;         dst[m][k] = *(const bf16x8*)(SA(b, hh) + lds_byte(wr * 64 + m * 16 + fr, k * 32 + fq * 8))
; #define LDB(dst, b, hh) _Pragma("unroll") for (int n = 0; n < 2; ++n) _Pragma("unroll") for (int k = 0; k < 2; ++k) \
;         dst[n][k] = *(const bf16x8*)(SB(b, hh) + lds_byte(wc * 32 + n * 16 + fr, k * 32 + fq * 8))
; #define MMA(ai, bj, At_, Bt_) do { __builtin_amdgcn_s_setprio(1); \
;         _Pragma("unroll") for (int m = 0; m < 4; ++m) _Pragma("unroll") for (int n = 0; n < 2; ++n) _Pragma("unroll") for (int k = 0; k < 2; ++k) \
;             acc[ai][bj][m][n] = MFMA16(At_[m][k], Bt_[n][k], acc[ai][bj][m][n]); \
;         __builtin_amdgcn_s_setprio(0); } while (0)
; #define WAIT_V(n) asm volatile("s_waitcnt vmcnt(" #n ")" ::: "memory")
; #define WAIT_L(n) asm volatile("s_waitcnt lgkmcnt(" #n ")" ::: "memory")
; #define BAR __builtin_amdgcn_s_barrier()
; #define SCHED __builtin_amdgcn_sched_barrier(0)
; #define WAIT_V(n) asm volatile("s_waitcnt vmcnt(" #n ")" ::: "memory")
; template <class Hook>
; DI void gemm8_cat3(f32x4 (&acc)[2][2][4][2], const bf16_t* R0, const bf16_t* R1, const bf16_t* R2, const bf16_t* C0, const bf16_t* C1, const bf16_t* C2, char* shm, Hook hook) {
;     ...
;     for (int tt = 8; tt < 16; tt += 2) {
;         LDB(B0, 0, 0); SCHED; LDA(At, 0, 0); STAGE(SA(1, 1), R, 128, tt + 1);
;         WAIT_L(8); BAR; WAIT_L(0); MMA(0, 0, At, B0); BAR; SCHED;
;         LDB(B1, 0, 1); STAGE(SB(0, 0), C, 0, tt + 2);
;         BAR; WAIT_L(0); MMA(0, 1, At, B1); BAR;
;         LDA(At, 0, 1); STAGE(SA(0, 0), R, 0, tt + 2);
;         BAR; WAIT_L(0); MMA(1, 0, At, B0); BAR; SCHED;
;         STAGE(SB(0, 1), C, 128, tt + 2);
;         WAIT_V(6); BAR; MMA(1, 1, At, B1); BAR;
;         LDB(B0, 1, 0); SCHED; LDA(At, 1, 0); STAGE(SA(0, 1), R, 128, tt + 2);
;         WAIT_L(8); BAR; WAIT_L(0); MMA(0, 0, At, B0); BAR; SCHED;
;         LDB(B1, 1, 1); STAGE(SB(1, 0), C, 0, tt + 3);
;         BAR; WAIT_L(0); MMA(0, 1, At, B1); BAR;
.LBB0_58:
	ds_read_b128 v[146:149], v189
	ds_read_b128 v[150:153], v189 offset:1024
	ds_read_b128 v[192:195], v189 offset:2048
	ds_read_b128 v[196:199], v189 offset:3072
	v_readfirstlane_b32 s35, v190
	s_mov_b32 m0, s35
	v_readfirstlane_b32 s35, v191
	ds_read_b128 v[200:203], v157
	ds_read_b128 v[204:207], v157 offset:1024
	ds_read_b128 v[208:211], v156
	ds_read_b128 v[212:215], v156 offset:1024
	ds_read_b128 v[216:219], v155
	ds_read_b128 v[220:223], v155 offset:1024
	ds_read_b128 v[224:227], v154
	ds_read_b128 v[228:231], v154 offset:1024
	global_load_lds_dwordx4 v[130:131], off
	s_mov_b32 m0, s35
	s_nop 0
	global_load_lds_dwordx4 v[132:133], off
	s_waitcnt lgkmcnt(8)
	s_barrier
	s_waitcnt lgkmcnt(0)
	s_setprio 1
	s_waitcnt lgkmcnt(0)
	v_mfma_f32_16x16x32_bf16 v[18:21], v[200:203], v[146:149], v[18:21]
	v_mfma_f32_16x16x32_bf16 v[58:61], v[200:203], v[192:195], v[58:61]
	v_mfma_f32_16x16x32_bf16 v[30:33], v[208:211], v[146:149], v[30:33]
	v_mfma_f32_16x16x32_bf16 v[54:57], v[208:211], v[192:195], v[54:57]
	v_mfma_f32_16x16x32_bf16 v[26:29], v[216:219], v[146:149], v[26:29]
	v_mfma_f32_16x16x32_bf16 v[50:53], v[216:219], v[192:195], v[50:53]
	v_mfma_f32_16x16x32_bf16 v[42:45], v[224:227], v[146:149], v[42:45]
	v_mfma_f32_16x16x32_bf16 v[46:49], v[224:227], v[192:195], v[46:49]
	v_mfma_f32_16x16x32_bf16 v[18:21], v[204:207], v[150:153], v[18:21]
	v_mfma_f32_16x16x32_bf16 v[58:61], v[204:207], v[196:199], v[58:61]
	v_mfma_f32_16x16x32_bf16 v[30:33], v[212:215], v[150:153], v[30:33]
	v_mfma_f32_16x16x32_bf16 v[54:57], v[212:215], v[196:199], v[54:57]
	v_mfma_f32_16x16x32_bf16 v[26:29], v[220:223], v[150:153], v[26:29]
	v_mfma_f32_16x16x32_bf16 v[50:53], v[220:223], v[196:199], v[50:53]
	v_mfma_f32_16x16x32_bf16 v[42:45], v[228:231], v[150:153], v[42:45]
	v_mfma_f32_16x16x32_bf16 v[46:49], v[228:231], v[196:199], v[46:49]
	s_setprio 0
	s_barrier
	s_sub_i32 s96, s9, 64
	s_add_i32 s35, s8, 4
	s_and_b32 s96, s96, 0x180
	s_and_b32 s35, s35, 24
	s_lshl_b32 vcc_lo, s96, 1
	s_cmp_eq_u32 s35, 8
	s_cselect_b32 s96, s25, s3
	s_cselect_b32 s35, s82, s34
	s_cselect_b32 vcc_hi, s24, s2
	s_cselect_b32 s44, s15, s26
	s_add_u32 s96, s96, vcc_lo
	s_addc_u32 s97, s35, 0
	v_readfirstlane_b32 s35, v159
	v_lshl_add_u64 v[172:173], s[96:97], 0, v[134:135]
	s_mov_b32 m0, s35
	v_readfirstlane_b32 s35, v160
	ds_read_b128 v[232:235], v188
	ds_read_b128 v[236:239], v188 offset:1024
	ds_read_b128 v[240:243], v188 offset:2048
	ds_read_b128 v[244:247], v188 offset:3072
	global_load_lds_dwordx4 v[172:173], off
	v_lshl_add_u64 v[172:173], s[96:97], 0, v[136:137]
	s_mov_b32 m0, s35
	s_nop 0
	global_load_lds_dwordx4 v[172:173], off
	s_barrier
	s_waitcnt lgkmcnt(0)
	s_setprio 1
	s_waitcnt lgkmcnt(0)
	v_mfma_f32_16x16x32_bf16 v[74:77], v[200:203], v[232:235], v[74:77]
	v_mfma_f32_16x16x32_bf16 v[90:93], v[200:203], v[240:243], v[90:93]
	v_mfma_f32_16x16x32_bf16 v[70:73], v[208:211], v[232:235], v[70:73]
	v_mfma_f32_16x16x32_bf16 v[86:89], v[208:211], v[240:243], v[86:89]
	v_mfma_f32_16x16x32_bf16 v[66:69], v[216:219], v[232:235], v[66:69]
	v_mfma_f32_16x16x32_bf16 v[82:85], v[216:219], v[240:243], v[82:85]
	v_mfma_f32_16x16x32_bf16 v[62:65], v[224:227], v[232:235], v[62:65]
	v_mfma_f32_16x16x32_bf16 v[78:81], v[224:227], v[240:243], v[78:81]
	v_mfma_f32_16x16x32_bf16 v[74:77], v[204:207], v[236:239], v[74:77]
	v_mfma_f32_16x16x32_bf16 v[90:93], v[204:207], v[244:247], v[90:93]
	v_mfma_f32_16x16x32_bf16 v[70:73], v[212:215], v[236:239], v[70:73]
	v_mfma_f32_16x16x32_bf16 v[86:89], v[212:215], v[244:247], v[86:89]
	v_mfma_f32_16x16x32_bf16 v[66:69], v[220:223], v[236:239], v[66:69]
	v_mfma_f32_16x16x32_bf16 v[82:85], v[220:223], v[244:247], v[82:85]
	v_mfma_f32_16x16x32_bf16 v[62:65], v[228:231], v[236:239], v[62:65]
	v_mfma_f32_16x16x32_bf16 v[78:81], v[228:231], v[244:247], v[78:81]
	s_setprio 0
	s_add_u32 vcc_lo, s44, vcc_lo
	s_addc_u32 vcc_hi, vcc_hi, 0
	v_readfirstlane_b32 s35, v158
	v_lshl_add_u64 v[172:173], vcc, 0, v[134:135]
	s_mov_b32 m0, s35
	v_readfirstlane_b32 s35, v164
	s_barrier
	ds_read_b128 v[200:203], v157 offset:16384
	ds_read_b128 v[204:207], v157 offset:17408
	ds_read_b128 v[208:211], v156 offset:16384
	ds_read_b128 v[212:215], v156 offset:17408
	ds_read_b128 v[216:219], v155 offset:16384
	ds_read_b128 v[220:223], v155 offset:17408
	ds_read_b128 v[224:227], v154 offset:16384
	ds_read_b128 v[228:231], v154 offset:17408
	global_load_lds_dwordx4 v[172:173], off
	v_lshl_add_u64 v[172:173], vcc, 0, v[136:137]
	s_mov_b32 m0, s35
	s_nop 0
	global_load_lds_dwordx4 v[172:173], off
	s_barrier
	s_waitcnt lgkmcnt(0)
	s_setprio 1
	s_waitcnt lgkmcnt(0)
	v_mfma_f32_16x16x32_bf16 v[106:109], v[200:203], v[146:149], v[106:109]
	v_mfma_f32_16x16x32_bf16 v[122:125], v[200:203], v[192:195], v[122:125]
	v_mfma_f32_16x16x32_bf16 v[102:105], v[208:211], v[146:149], v[102:105]
	v_mfma_f32_16x16x32_bf16 v[118:121], v[208:211], v[192:195], v[118:121]
	v_mfma_f32_16x16x32_bf16 v[98:101], v[216:219], v[146:149], v[98:101]
	v_mfma_f32_16x16x32_bf16 v[114:117], v[216:219], v[192:195], v[114:117]
	v_mfma_f32_16x16x32_bf16 v[94:97], v[224:227], v[146:149], v[94:97]
	v_mfma_f32_16x16x32_bf16 v[110:113], v[224:227], v[192:195], v[110:113]
	v_mfma_f32_16x16x32_bf16 v[106:109], v[204:207], v[150:153], v[106:109]
	v_mfma_f32_16x16x32_bf16 v[122:125], v[204:207], v[196:199], v[122:125]
	v_mfma_f32_16x16x32_bf16 v[102:105], v[212:215], v[150:153], v[102:105]
	v_mfma_f32_16x16x32_bf16 v[118:121], v[212:215], v[196:199], v[118:121]
	v_mfma_f32_16x16x32_bf16 v[98:101], v[220:223], v[150:153], v[98:101]
	v_mfma_f32_16x16x32_bf16 v[114:117], v[220:223], v[196:199], v[114:117]
	v_mfma_f32_16x16x32_bf16 v[94:97], v[228:231], v[150:153], v[94:97]
	v_mfma_f32_16x16x32_bf16 v[110:113], v[228:231], v[196:199], v[110:113]
	s_setprio 0
	s_barrier
; #define STAGE(P, BASE, br, kt) do { const bf16_t* g_ = (BASE) + (size_t)(br) * K + (size_t)(kt) * 64; \
;         _Pragma("unroll") for (int i_ = 0; i_ < 2; ++i_) \
;             __builtin_amdgcn_global_load_lds((const unsigned*)(g_ + gofs[i_]), (lds_ptr_t)((P) + wb + i_ * 8192), 16, 0, 0); } while (0)
; #define LDA(dst, b, hh) _Pragma("unroll") for (int m = 0; m < 4; ++m) _Pragma("unroll") for (int k = 0; k < 2; ++k) \
;         dst[m][k] = *(const bf16x8*)(SA(b, hh) + lds_byte(wr * 64 + m * 16 + fr, k * 32 + fq * 8))
; #define LDB(dst, b, hh) _Pragma("unroll") for (int n = 0; n < 2; ++n) _Pragma("unroll") for (int k = 0; k < 2; ++k) \
;         dst[n][k] = *(const bf16x8*)(SB(b, hh) + lds_byte(wc * 32 + n * 16 + fr, k * 32 + fq * 8))
; #define MMA(ai, bj, At_, Bt_) do { __builtin_amdgcn_s_setprio(1); \
;         _Pragma("unroll") for (int m = 0; m < 4; ++m) _Pragma("unroll") for (int n = 0; n < 2; ++n) _Pragma("unroll") for (int k = 0; k < 2; ++k) \
;             acc[ai][bj][m][n] = MFMA16(At_[m][k], Bt_[n][k], acc[ai][bj][m][n]); \
;         __builtin_amdgcn_s_setprio(0); } while (0)
; #define WAIT_V(n) asm volatile("s_waitcnt vmcnt(" #n ")" ::: "memory")
; #define WAIT_L(n) asm volatile("s_waitcnt lgkmcnt(" #n ")" ::: "memory")
; #define BAR __builtin_amdgcn_s_barrier()
; #define SCHED __builtin_amdgcn_sched_barrier(0)
; #define LDA(dst, b, hh) _Pragma("unroll") for (int m = 0; m < 4; ++m) _Pragma("unroll") for (int k = 0; k < 2; ++k) \
;         dst[m][k] = *(const bf16x8*)(SA(b, hh) + lds_byte(wr * 64 + m * 16 + fr, k * 32 + fq * 8))
; template <class Hook>
; DI void gemm8_cat3(f32x4 (&acc)[2][2][4][2], const bf16_t* R0, const bf16_t* R1, const bf16_t* R2, const bf16_t* C0, const bf16_t* C1, const bf16_t* C2, char* shm, Hook hook) {
;     ...
;         LDA(At, 0, 1); STAGE(SA(0, 0), R, 0, tt + 2);
;         BAR; WAIT_L(0); MMA(1, 0, At, B0); BAR; SCHED;
;         STAGE(SB(0, 1), C, 128, tt + 2);
;         WAIT_V(6); BAR; MMA(1, 1, At, B1); BAR;
;         LDB(B0, 1, 0); SCHED; LDA(At, 1, 0); STAGE(SA(0, 1), R, 128, tt + 2);
;         WAIT_L(8); BAR; WAIT_L(0); MMA(0, 0, At, B0); BAR; SCHED;
;         LDB(B1, 1, 1); STAGE(SB(1, 0), C, 0, tt + 3);
;         BAR; WAIT_L(0); MMA(0, 1, At, B1); BAR;
;         LDA(At, 1, 1); STAGE(SA(1, 0), R, 0, tt + 3);
;         BAR; WAIT_L(0); MMA(1, 0, At, B0); BAR; SCHED;
;         STAGE(SB(1, 1), C, 128, tt + 3);
	s_add_u32 s96, s96, 0x20000
	s_addc_u32 s97, s97, 0
	v_readfirstlane_b32 s35, v165
	v_lshl_add_u64 v[146:147], s[96:97], 0, v[134:135]
	s_mov_b32 m0, s35
	v_readfirstlane_b32 s35, v166
	global_load_lds_dwordx4 v[146:147], off
	v_lshl_add_u64 v[146:147], s[96:97], 0, v[136:137]
	s_mov_b32 m0, s35
	s_nop 0
	global_load_lds_dwordx4 v[146:147], off
	s_waitcnt vmcnt(6)
	s_barrier
	s_setprio 1
	v_mfma_f32_16x16x32_bf16 v[126:129], v[200:203], v[232:235], v[126:129]
	v_mfma_f32_16x16x32_bf16 v[14:17], v[200:203], v[240:243], v[14:17]
	v_mfma_f32_16x16x32_bf16 v[34:37], v[208:211], v[232:235], v[34:37]
	v_mfma_f32_16x16x32_bf16 v[6:9], v[208:211], v[240:243], v[6:9]
	v_mfma_f32_16x16x32_bf16 v[38:41], v[216:219], v[232:235], v[38:41]
	v_mfma_f32_16x16x32_bf16 v[10:13], v[216:219], v[240:243], v[10:13]
	v_mfma_f32_16x16x32_bf16 v[22:25], v[224:227], v[232:235], v[22:25]
	v_mfma_f32_16x16x32_bf16 v[2:5], v[224:227], v[240:243], v[2:5]
	v_mfma_f32_16x16x32_bf16 v[126:129], v[204:207], v[236:239], v[126:129]
	v_mfma_f32_16x16x32_bf16 v[14:17], v[204:207], v[244:247], v[14:17]
	v_mfma_f32_16x16x32_bf16 v[34:37], v[212:215], v[236:239], v[34:37]
	v_mfma_f32_16x16x32_bf16 v[6:9], v[212:215], v[244:247], v[6:9]
	v_mfma_f32_16x16x32_bf16 v[38:41], v[220:223], v[236:239], v[38:41]
	v_mfma_f32_16x16x32_bf16 v[10:13], v[220:223], v[244:247], v[10:13]
	v_mfma_f32_16x16x32_bf16 v[22:25], v[228:231], v[236:239], v[22:25]
	v_mfma_f32_16x16x32_bf16 v[2:5], v[228:231], v[244:247], v[2:5]
	s_setprio 0
	s_barrier
	ds_read_b128 v[146:149], v169
	ds_read_b128 v[150:153], v169 offset:1024
	ds_read_b128 v[192:195], v169 offset:2048
	ds_read_b128 v[196:199], v169 offset:3072
	s_add_u32 s96, vcc_lo, 0x20000
	s_addc_u32 s97, vcc_hi, 0
	v_readfirstlane_b32 s35, v167
	v_lshl_add_u64 v[172:173], s[96:97], 0, v[134:135]
	s_mov_b32 m0, s35
	v_readfirstlane_b32 s35, v168
	ds_read_b128 v[200:203], v157 offset:32768
	ds_read_b128 v[204:207], v157 offset:33792
	ds_read_b128 v[208:211], v156 offset:32768
	ds_read_b128 v[212:215], v156 offset:33792
	ds_read_b128 v[216:219], v155 offset:32768
	ds_read_b128 v[220:223], v155 offset:33792
	ds_read_b128 v[224:227], v154 offset:32768
	ds_read_b128 v[228:231], v154 offset:33792
	global_load_lds_dwordx4 v[172:173], off
	v_lshl_add_u64 v[172:173], s[96:97], 0, v[136:137]
	s_mov_b32 m0, s35
	s_nop 0
	global_load_lds_dwordx4 v[172:173], off
	s_waitcnt lgkmcnt(8)
	s_barrier
	s_waitcnt lgkmcnt(0)
	s_setprio 1
	s_waitcnt lgkmcnt(0)
	v_mfma_f32_16x16x32_bf16 v[18:21], v[200:203], v[146:149], v[18:21]
	v_mfma_f32_16x16x32_bf16 v[58:61], v[200:203], v[192:195], v[58:61]
	v_mfma_f32_16x16x32_bf16 v[30:33], v[208:211], v[146:149], v[30:33]
	v_mfma_f32_16x16x32_bf16 v[54:57], v[208:211], v[192:195], v[54:57]
	v_mfma_f32_16x16x32_bf16 v[26:29], v[216:219], v[146:149], v[26:29]
	v_mfma_f32_16x16x32_bf16 v[50:53], v[216:219], v[192:195], v[50:53]
	v_mfma_f32_16x16x32_bf16 v[42:45], v[224:227], v[146:149], v[42:45]
	v_mfma_f32_16x16x32_bf16 v[46:49], v[224:227], v[192:195], v[46:49]
	v_mfma_f32_16x16x32_bf16 v[18:21], v[204:207], v[150:153], v[18:21]
	v_mfma_f32_16x16x32_bf16 v[58:61], v[204:207], v[196:199], v[58:61]
	v_mfma_f32_16x16x32_bf16 v[30:33], v[212:215], v[150:153], v[30:33]
	v_mfma_f32_16x16x32_bf16 v[54:57], v[212:215], v[196:199], v[54:57]
	v_mfma_f32_16x16x32_bf16 v[26:29], v[220:223], v[150:153], v[26:29]
	v_mfma_f32_16x16x32_bf16 v[50:53], v[220:223], v[196:199], v[50:53]
	v_mfma_f32_16x16x32_bf16 v[42:45], v[228:231], v[150:153], v[42:45]
	v_mfma_f32_16x16x32_bf16 v[46:49], v[228:231], v[196:199], v[46:49]
	s_setprio 0
	s_barrier
	s_add_i32 s35, s8, 5
	s_and_b32 s44, s9, 0x1c0
	s_and_b32 s35, s35, 24
	s_lshl_b32 s44, s44, 1
	s_cmp_eq_u32 s35, 8
	s_cselect_b32 s45, s25, s3
	s_cselect_b32 s35, s82, s34
	s_cselect_b32 vcc_hi, s24, s2
	s_cselect_b32 vcc_lo, s15, s26
	s_add_u32 s96, s45, s44
	s_addc_u32 s97, s35, 0
	v_readfirstlane_b32 s35, v170
	v_lshl_add_u64 v[172:173], s[96:97], 0, v[134:135]
	s_mov_b32 m0, s35
	v_readfirstlane_b32 s35, v171
	ds_read_b128 v[232:235], v161
	ds_read_b128 v[236:239], v161 offset:1024
	ds_read_b128 v[240:243], v161 offset:2048
	ds_read_b128 v[244:247], v161 offset:3072
	global_load_lds_dwordx4 v[172:173], off
	v_lshl_add_u64 v[172:173], s[96:97], 0, v[136:137]
	s_mov_b32 m0, s35
	s_nop 0
	global_load_lds_dwordx4 v[172:173], off
	s_barrier
	s_waitcnt lgkmcnt(0)
	s_setprio 1
	s_waitcnt lgkmcnt(0)
	v_mfma_f32_16x16x32_bf16 v[74:77], v[200:203], v[232:235], v[74:77]
	v_mfma_f32_16x16x32_bf16 v[90:93], v[200:203], v[240:243], v[90:93]
	v_mfma_f32_16x16x32_bf16 v[70:73], v[208:211], v[232:235], v[70:73]
	v_mfma_f32_16x16x32_bf16 v[86:89], v[208:211], v[240:243], v[86:89]
	v_mfma_f32_16x16x32_bf16 v[66:69], v[216:219], v[232:235], v[66:69]
	v_mfma_f32_16x16x32_bf16 v[82:85], v[216:219], v[240:243], v[82:85]
	v_mfma_f32_16x16x32_bf16 v[62:65], v[224:227], v[232:235], v[62:65]
	v_mfma_f32_16x16x32_bf16 v[78:81], v[224:227], v[240:243], v[78:81]
	v_mfma_f32_16x16x32_bf16 v[74:77], v[204:207], v[236:239], v[74:77]
	v_mfma_f32_16x16x32_bf16 v[90:93], v[204:207], v[244:247], v[90:93]
	v_mfma_f32_16x16x32_bf16 v[70:73], v[212:215], v[236:239], v[70:73]
	v_mfma_f32_16x16x32_bf16 v[86:89], v[212:215], v[244:247], v[86:89]
	v_mfma_f32_16x16x32_bf16 v[66:69], v[220:223], v[236:239], v[66:69]
	v_mfma_f32_16x16x32_bf16 v[82:85], v[220:223], v[244:247], v[82:85]
	v_mfma_f32_16x16x32_bf16 v[62:65], v[228:231], v[236:239], v[62:65]
	v_mfma_f32_16x16x32_bf16 v[78:81], v[228:231], v[244:247], v[78:81]
	s_setprio 0
	s_add_u32 vcc_lo, vcc_lo, s44
	s_addc_u32 vcc_hi, vcc_hi, 0
	v_readfirstlane_b32 s35, v184
	v_lshl_add_u64 v[172:173], vcc, 0, v[134:135]
	s_mov_b32 m0, s35
	v_readfirstlane_b32 s35, v185
	s_barrier
; DI float frcp(float x) { return __builtin_amdgcn_rcpf(x); }
; #define STAGE(P, BASE, br, kt) do { const bf16_t* g_ = (BASE) + (size_t)(br) * K + (size_t)(kt) * 64; \
;         _Pragma("unroll") for (int i_ = 0; i_ < 2; ++i_) \
;             __builtin_amdgcn_global_load_lds((const unsigned*)(g_ + gofs[i_]), (lds_ptr_t)((P) + wb + i_ * 8192), 16, 0, 0); } while (0)
; #define LDA(dst, b, hh) _Pragma("unroll") for (int m = 0; m < 4; ++m) _Pragma("unroll") for (int k = 0; k < 2; ++k) \
;         dst[m][k] = *(const bf16x8*)(SA(b, hh) + lds_byte(wr * 64 + m * 16 + fr, k * 32 + fq * 8))
; #define MMA(ai, bj, At_, Bt_) do { __builtin_amdgcn_s_setprio(1); \
;         _Pragma("unroll") for (int m = 0; m < 4; ++m) _Pragma("unroll") for (int n = 0; n < 2; ++n) _Pragma("unroll") for (int k = 0; k < 2; ++k) \
;             acc[ai][bj][m][n] = MFMA16(At_[m][k], Bt_[n][k], acc[ai][bj][m][n]); \
;         __builtin_amdgcn_s_setprio(0); } while (0)
; #define WAIT_V(n) asm volatile("s_waitcnt vmcnt(" #n ")" ::: "memory")
; #define WAIT_L(n) asm volatile("s_waitcnt lgkmcnt(" #n ")" ::: "memory")
; #define BAR __builtin_amdgcn_s_barrier()
; template <class Hook>
; DI void gemm8_cat3(f32x4 (&acc)[2][2][4][2], const bf16_t* R0, const bf16_t* R1, const bf16_t* R2, const bf16_t* C0, const bf16_t* C1, const bf16_t* C2, char* shm, Hook hook) {
;     ...
;         LDA(At, 1, 1); STAGE(SA(1, 0), R, 0, tt + 3);
;         BAR; WAIT_L(0); MMA(1, 0, At, B0); BAR; SCHED;
;         STAGE(SB(1, 1), C, 128, tt + 3);
;         WAIT_V(6); BAR; MMA(1, 1, At, B1); BAR;
;     }
;     hook(1);
; DI void merge_scale(const Params& P, int tile, int seg, f32x4 (&acc)[2][2][4][2]) {
; #pragma unroll
;     for (int g8 = 0; g8 < 8; ++g8) {
;         const int ai = g8 >> 2, bj = (g8 >> 1) & 1, nn = g8 & 1;
;         const u32x4 ga = *gate_slot(P, tile, seg, g8), gb = *gate_slot(P, tile, seg + 1, g8);
; #pragma unroll
;         for (int e = 0; e < 8; ++e) {
;             const float rl = (float)((ga[e >> 2] >> (8 * (e & 3))) & 255u) * frcp((float)((gb[e >> 2] >> (8 * (e & 3))) & 255u));
;             const float rh = (float)((ga[2 + (e >> 2)] >> (8 * (e & 3))) & 255u) * frcp((float)((gb[2 + (e >> 2)] >> (8 * (e & 3))) & 255u));
;             acc[ai][bj][e >> 2][nn][e & 3] *= rl;
;             acc[ai][bj][2 + (e >> 2)][nn][e & 3] *= rh;
;         }
;         __builtin_amdgcn_sched_barrier(0);
;     }
; }
	ds_read_b128 v[200:203], v157 offset:49152
	ds_read_b128 v[204:207], v157 offset:50176
	ds_read_b128 v[208:211], v156 offset:49152
	ds_read_b128 v[212:215], v156 offset:50176
	ds_read_b128 v[216:219], v155 offset:49152
	ds_read_b128 v[220:223], v155 offset:50176
	ds_read_b128 v[224:227], v154 offset:49152
	ds_read_b128 v[228:231], v154 offset:50176
	global_load_lds_dwordx4 v[172:173], off
	v_lshl_add_u64 v[172:173], vcc, 0, v[136:137]
	s_mov_b32 m0, s35
	s_nop 0
	global_load_lds_dwordx4 v[172:173], off
	s_barrier
	s_waitcnt lgkmcnt(0)
	s_setprio 1
	s_waitcnt lgkmcnt(0)
	v_mfma_f32_16x16x32_bf16 v[106:109], v[200:203], v[146:149], v[106:109]
	v_mfma_f32_16x16x32_bf16 v[122:125], v[200:203], v[192:195], v[122:125]
	v_mfma_f32_16x16x32_bf16 v[102:105], v[208:211], v[146:149], v[102:105]
	v_mfma_f32_16x16x32_bf16 v[118:121], v[208:211], v[192:195], v[118:121]
	v_mfma_f32_16x16x32_bf16 v[98:101], v[216:219], v[146:149], v[98:101]
	v_mfma_f32_16x16x32_bf16 v[114:117], v[216:219], v[192:195], v[114:117]
	v_mfma_f32_16x16x32_bf16 v[94:97], v[224:227], v[146:149], v[94:97]
	v_mfma_f32_16x16x32_bf16 v[110:113], v[224:227], v[192:195], v[110:113]
	v_mfma_f32_16x16x32_bf16 v[106:109], v[204:207], v[150:153], v[106:109]
	v_mfma_f32_16x16x32_bf16 v[122:125], v[204:207], v[196:199], v[122:125]
	v_mfma_f32_16x16x32_bf16 v[102:105], v[212:215], v[150:153], v[102:105]
	v_mfma_f32_16x16x32_bf16 v[118:121], v[212:215], v[196:199], v[118:121]
	v_mfma_f32_16x16x32_bf16 v[98:101], v[220:223], v[150:153], v[98:101]
	v_mfma_f32_16x16x32_bf16 v[114:117], v[220:223], v[196:199], v[114:117]
	v_mfma_f32_16x16x32_bf16 v[94:97], v[228:231], v[150:153], v[94:97]
	v_mfma_f32_16x16x32_bf16 v[110:113], v[228:231], v[196:199], v[110:113]
	s_setprio 0
	s_barrier
	s_add_u32 s96, s96, 0x20000
	s_addc_u32 s97, s97, 0
	v_readfirstlane_b32 s35, v186
	v_lshl_add_u64 v[146:147], s[96:97], 0, v[134:135]
	s_mov_b32 m0, s35
	v_readfirstlane_b32 s35, v187
	global_load_lds_dwordx4 v[146:147], off
	v_lshl_add_u64 v[146:147], s[96:97], 0, v[136:137]
	s_mov_b32 m0, s35
	s_nop 0
	global_load_lds_dwordx4 v[146:147], off
	s_waitcnt vmcnt(6)
	s_barrier
	s_setprio 1
	v_mfma_f32_16x16x32_bf16 v[126:129], v[200:203], v[232:235], v[126:129]
	v_mfma_f32_16x16x32_bf16 v[14:17], v[200:203], v[240:243], v[14:17]
	v_mfma_f32_16x16x32_bf16 v[34:37], v[208:211], v[232:235], v[34:37]
	v_mfma_f32_16x16x32_bf16 v[6:9], v[208:211], v[240:243], v[6:9]
	v_mfma_f32_16x16x32_bf16 v[38:41], v[216:219], v[232:235], v[38:41]
	v_mfma_f32_16x16x32_bf16 v[10:13], v[216:219], v[240:243], v[10:13]
	v_mfma_f32_16x16x32_bf16 v[22:25], v[224:227], v[232:235], v[22:25]
	v_mfma_f32_16x16x32_bf16 v[2:5], v[224:227], v[240:243], v[2:5]
	v_mfma_f32_16x16x32_bf16 v[126:129], v[204:207], v[236:239], v[126:129]
	v_mfma_f32_16x16x32_bf16 v[14:17], v[204:207], v[244:247], v[14:17]
	v_mfma_f32_16x16x32_bf16 v[34:37], v[212:215], v[236:239], v[34:37]
	v_mfma_f32_16x16x32_bf16 v[6:9], v[212:215], v[244:247], v[6:9]
	v_mfma_f32_16x16x32_bf16 v[38:41], v[220:223], v[236:239], v[38:41]
	v_mfma_f32_16x16x32_bf16 v[10:13], v[220:223], v[244:247], v[10:13]
	v_mfma_f32_16x16x32_bf16 v[22:25], v[228:231], v[236:239], v[22:25]
	v_mfma_f32_16x16x32_bf16 v[2:5], v[228:231], v[244:247], v[2:5]
	s_setprio 0
	s_add_i32 s8, s8, 2
	s_addk_i32 s9, 0x80
	v_lshl_add_u64 v[130:131], v[130:131], 0, s[90:91]
	s_cmp_lt_u32 s8, 14
	v_lshl_add_u64 v[132:133], v[132:133], 0, s[90:91]
	s_barrier
	s_cbranch_scc1 .LBB0_58
	s_lshl_b64 s[8:9], s[58:59], 16
	v_mov_b32_e32 v130, v162
	s_add_u32 s35, s8, 0x20000
	s_addc_u32 s44, s9, 0
	v_ashrrev_i32_e32 v131, 31, v130
	v_lshl_add_u64 v[130:131], v[130:131], 4, s[56:57]
	v_mov_b32_e32 v134, v162
	s_add_u32 s8, s74, s35
	v_mov_b64_e32 v[242:243], v[130:131]
	s_addc_u32 s9, s75, s44
	v_ashrrev_i32_e32 v135, 31, v134
	v_lshl_add_u64 v[134:135], v[134:135], 4, s[8:9]
	v_mov_b64_e32 v[244:245], v[134:135]
	s_mov_b64 s[0:1], 0x2000
	global_load_dwordx4 v[210:213], v[242:243], off
	v_lshl_add_u64 v[242:243], v[242:243], 0, s[0:1]
	global_load_dwordx4 v[226:229], v[244:245], off
	v_lshl_add_u64 v[244:245], v[244:245], 0, s[0:1]
	global_load_dwordx4 v[214:217], v[242:243], off
	v_lshl_add_u64 v[242:243], v[242:243], 0, s[0:1]
	global_load_dwordx4 v[230:233], v[244:245], off
	v_lshl_add_u64 v[244:245], v[244:245], 0, s[0:1]
	global_load_dwordx4 v[218:221], v[242:243], off
	v_lshl_add_u64 v[242:243], v[242:243], 0, s[0:1]
	global_load_dwordx4 v[234:237], v[244:245], off
	v_lshl_add_u64 v[244:245], v[244:245], 0, s[0:1]
	global_load_dwordx4 v[222:225], v[242:243], off
	v_lshl_add_u64 v[242:243], v[242:243], 0, s[0:1]
	global_load_dwordx4 v[238:241], v[244:245], off
	v_lshl_add_u64 v[244:245], v[244:245], 0, s[0:1]
	s_waitcnt vmcnt(7)
	s_nop 1
	v_mov_b64_e32 v[130:131], v[210:211]
	v_mov_b64_e32 v[132:133], v[212:213]
	v_cvt_f32_ubyte3_e32 v147, v130
	v_cvt_f32_ubyte2_e32 v146, v130
	v_cvt_f32_ubyte1_e32 v149, v130
	v_cvt_f32_ubyte0_e32 v148, v130
	v_cvt_f32_ubyte3_e32 v151, v132
	v_cvt_f32_ubyte2_e32 v150, v132
	v_cvt_f32_ubyte1_e32 v153, v132
	v_cvt_f32_ubyte0_e32 v152, v132
	v_cvt_f32_ubyte3_e32 v173, v131
	v_cvt_f32_ubyte2_e32 v172, v131
	v_cvt_f32_ubyte1_e32 v193, v131
	v_cvt_f32_ubyte0_e32 v192, v131
	v_cvt_f32_ubyte3_e32 v131, v133
	v_cvt_f32_ubyte2_e32 v130, v133
	v_cvt_f32_ubyte1_e32 v195, v133
	v_cvt_f32_ubyte0_e32 v194, v133
	s_waitcnt vmcnt(6)
; DI float frcp(float x) { return __builtin_amdgcn_rcpf(x); }
; DI u32x4* gate_slot(const Params& P, int tile, int j, int g8) { return (u32x4*)slotp(P, SL_SK) + ((size_t)(tile * 3 + j) * 8 + g8) * 512 + tid(); }
; DI void merge_scale(const Params& P, int tile, int seg, f32x4 (&acc)[2][2][4][2]) {
; #pragma unroll
;     for (int g8 = 0; g8 < 8; ++g8) {
;         const int ai = g8 >> 2, bj = (g8 >> 1) & 1, nn = g8 & 1;
;         const u32x4 ga = *gate_slot(P, tile, seg, g8), gb = *gate_slot(P, tile, seg + 1, g8);
; #pragma unroll
;         for (int e = 0; e < 8; ++e) {
;             const float rl = (float)((ga[e >> 2] >> (8 * (e & 3))) & 255u) * frcp((float)((gb[e >> 2] >> (8 * (e & 3))) & 255u));
;             const float rh = (float)((ga[2 + (e >> 2)] >> (8 * (e & 3))) & 255u) * frcp((float)((gb[2 + (e >> 2)] >> (8 * (e & 3))) & 255u));
;             acc[ai][bj][e >> 2][nn][e & 3] *= rl;
;             acc[ai][bj][2 + (e >> 2)][nn][e & 3] *= rh;
;         }
;         __builtin_amdgcn_sched_barrier(0);
;     }
; }
	s_nop 1
	v_mov_b64_e32 v[134:135], v[226:227]
	v_mov_b64_e32 v[136:137], v[228:229]
	v_cvt_f32_ubyte0_e32 v132, v134
	v_cvt_f32_ubyte0_e32 v133, v136
	v_cvt_f32_ubyte1_e32 v196, v134
	v_cvt_f32_ubyte1_e32 v197, v136
	v_cvt_f32_ubyte2_e32 v198, v134
	v_cvt_f32_ubyte2_e32 v199, v136
	v_cvt_f32_ubyte3_e32 v200, v134
	v_cvt_f32_ubyte3_e32 v201, v136
	v_cvt_f32_ubyte0_e32 v202, v135
	v_cvt_f32_ubyte0_e32 v203, v137
	v_cvt_f32_ubyte1_e32 v204, v135
	v_cvt_f32_ubyte1_e32 v205, v137
	v_cvt_f32_ubyte2_e32 v206, v135
	v_cvt_f32_ubyte2_e32 v207, v137
	v_cvt_f32_ubyte3_e32 v208, v135
	v_cvt_f32_ubyte3_e32 v209, v137
	v_rcp_iflag_f32_e32 v132, v132
	v_rcp_iflag_f32_e32 v134, v133
	v_rcp_iflag_f32_e32 v133, v196
	v_rcp_iflag_f32_e32 v135, v197
	v_rcp_iflag_f32_e32 v136, v198
	v_rcp_iflag_f32_e32 v196, v199
	v_rcp_iflag_f32_e32 v137, v200
	v_rcp_iflag_f32_e32 v197, v201
	v_rcp_iflag_f32_e32 v198, v202
	v_rcp_iflag_f32_e32 v200, v203
	v_rcp_iflag_f32_e32 v199, v204
	v_rcp_iflag_f32_e32 v201, v205
	v_rcp_iflag_f32_e32 v202, v206
	v_rcp_iflag_f32_e32 v204, v207
	v_rcp_iflag_f32_e32 v203, v208
	v_rcp_iflag_f32_e32 v205, v209
	v_pk_mul_f32 v[148:149], v[132:133], v[148:149]
	v_pk_mul_f32 v[132:133], v[136:137], v[146:147]
	v_pk_mul_f32 v[134:135], v[134:135], v[152:153]
	v_pk_mul_f32 v[136:137], v[196:197], v[150:151]
	v_pk_mul_f32 v[146:147], v[198:199], v[192:193]
	v_pk_mul_f32 v[150:151], v[202:203], v[172:173]
	v_pk_mul_f32 v[152:153], v[200:201], v[194:195]
	v_pk_mul_f32 v[172:173], v[204:205], v[130:131]
	v_pk_mul_f32 v[132:133], v[20:21], v[132:133]
	v_pk_mul_f32 v[130:131], v[18:19], v[148:149]
	v_pk_mul_f32 v[20:21], v[28:29], v[136:137]
	v_pk_mul_f32 v[18:19], v[26:27], v[134:135]
	v_pk_mul_f32 v[32:33], v[32:33], v[150:151]
	v_pk_mul_f32 v[30:31], v[30:31], v[146:147]
	v_pk_mul_f32 v[28:29], v[44:45], v[172:173]
	v_pk_mul_f32 v[26:27], v[42:43], v[152:153]
	v_mov_b32_e32 v42, v162
	s_add_u32 s35, s62, s35
	v_ashrrev_i32_e32 v43, 31, v42
	v_lshl_add_u64 v[42:43], v[42:43], 4, s[54:55]
	s_addc_u32 vcc_lo, s63, s44
	s_add_u32 s58, s35, 0x13802000
	v_mov_b32_e32 v42, v162
	s_addc_u32 s59, vcc_lo, 0
	v_ashrrev_i32_e32 v43, 31, v42
	v_lshl_add_u64 v[42:43], v[42:43], 4, s[58:59]
	s_waitcnt vmcnt(5)
	s_nop 1
	v_mov_b64_e32 v[134:135], v[214:215]
	v_mov_b64_e32 v[136:137], v[216:217]
	v_cvt_f32_ubyte3_e32 v173, v134
	v_cvt_f32_ubyte2_e32 v172, v134
	v_cvt_f32_ubyte1_e32 v193, v134
	v_cvt_f32_ubyte0_e32 v192, v134
	s_waitcnt vmcnt(4)
	s_nop 1
	v_mov_b64_e32 v[146:147], v[230:231]
	v_mov_b64_e32 v[148:149], v[232:233]
	v_cvt_f32_ubyte0_e32 v43, v148
	v_cvt_f32_ubyte1_e32 v44, v148
	v_cvt_f32_ubyte2_e32 v45, v148
	v_cvt_f32_ubyte0_e32 v42, v146
	v_rcp_iflag_f32_e32 v150, v43
	v_cvt_f32_ubyte1_e32 v43, v146
	v_rcp_iflag_f32_e32 v151, v44
	v_cvt_f32_ubyte2_e32 v44, v146
	v_rcp_iflag_f32_e32 v152, v45
	v_cvt_f32_ubyte3_e32 v45, v146
	v_rcp_iflag_f32_e32 v42, v42
	v_rcp_iflag_f32_e32 v43, v43
	v_rcp_iflag_f32_e32 v44, v44
	v_rcp_iflag_f32_e32 v45, v45
	v_cvt_f32_ubyte3_e32 v146, v148
	v_rcp_iflag_f32_e32 v153, v146
	v_pk_mul_f32 v[42:43], v[42:43], v[192:193]
	v_pk_mul_f32 v[44:45], v[44:45], v[172:173]
	v_pk_mul_f32 v[42:43], v[58:59], v[42:43]
	v_pk_mul_f32 v[44:45], v[60:61], v[44:45]
	v_cvt_f32_ubyte3_e32 v59, v136
	v_cvt_f32_ubyte2_e32 v58, v136
	v_cvt_f32_ubyte1_e32 v61, v136
	v_cvt_f32_ubyte0_e32 v60, v136
	v_pk_mul_f32 v[60:61], v[150:151], v[60:61]
	v_pk_mul_f32 v[58:59], v[152:153], v[58:59]
	v_pk_mul_f32 v[50:51], v[50:51], v[60:61]
	v_pk_mul_f32 v[52:53], v[52:53], v[58:59]
	v_cvt_f32_ubyte0_e32 v58, v147
	v_cvt_f32_ubyte1_e32 v59, v147
	v_cvt_f32_ubyte2_e32 v60, v147
	v_cvt_f32_ubyte3_e32 v61, v147
	v_rcp_iflag_f32_e32 v150, v58
	v_rcp_iflag_f32_e32 v151, v59
	v_rcp_iflag_f32_e32 v146, v60
	v_rcp_iflag_f32_e32 v147, v61
	v_cvt_f32_ubyte0_e32 v58, v149
	v_cvt_f32_ubyte1_e32 v59, v149
	v_cvt_f32_ubyte2_e32 v60, v149
	v_cvt_f32_ubyte3_e32 v61, v149
	v_rcp_iflag_f32_e32 v58, v58
	v_rcp_iflag_f32_e32 v59, v59
	v_rcp_iflag_f32_e32 v60, v60
	v_rcp_iflag_f32_e32 v61, v61
	v_cvt_f32_ubyte3_e32 v149, v135
	v_cvt_f32_ubyte2_e32 v148, v135
	v_cvt_f32_ubyte1_e32 v153, v135
	v_cvt_f32_ubyte0_e32 v152, v135
	v_pk_mul_f32 v[134:135], v[150:151], v[152:153]
	v_pk_mul_f32 v[146:147], v[146:147], v[148:149]
	v_pk_mul_f32 v[54:55], v[54:55], v[134:135]
	v_pk_mul_f32 v[56:57], v[56:57], v[146:147]
	v_cvt_f32_ubyte3_e32 v135, v137
	v_cvt_f32_ubyte2_e32 v134, v137
	v_cvt_f32_ubyte1_e32 v147, v137
	v_cvt_f32_ubyte0_e32 v146, v137
	v_pk_mul_f32 v[58:59], v[58:59], v[146:147]
	v_pk_mul_f32 v[60:61], v[60:61], v[134:135]
	v_pk_mul_f32 v[46:47], v[46:47], v[58:59]
	v_pk_mul_f32 v[48:49], v[48:49], v[60:61]
	v_mov_b32_e32 v58, v162
	s_add_u32 s56, s35, 0x13804000
	v_ashrrev_i32_e32 v59, 31, v58
	v_lshl_add_u64 v[58:59], v[58:59], 4, s[6:7]
	v_mov_b32_e32 v58, v162
	s_addc_u32 s57, vcc_lo, 0
	v_ashrrev_i32_e32 v59, 31, v58
	v_lshl_add_u64 v[58:59], v[58:59], 4, s[56:57]
	s_waitcnt vmcnt(3)
	s_nop 1
	v_mov_b64_e32 v[134:135], v[218:219]
	v_mov_b64_e32 v[136:137], v[220:221]
	v_cvt_f32_ubyte3_e32 v173, v134
	v_cvt_f32_ubyte2_e32 v172, v134
	v_cvt_f32_ubyte1_e32 v193, v134
	v_cvt_f32_ubyte0_e32 v192, v134
	s_waitcnt vmcnt(2)
; DI float frcp(float x) { return __builtin_amdgcn_rcpf(x); }
; DI u32x4* gate_slot(const Params& P, int tile, int j, int g8) { return (u32x4*)slotp(P, SL_SK) + ((size_t)(tile * 3 + j) * 8 + g8) * 512 + tid(); }
; DI void merge_scale(const Params& P, int tile, int seg, f32x4 (&acc)[2][2][4][2]) {
; #pragma unroll
;     for (int g8 = 0; g8 < 8; ++g8) {
;         const int ai = g8 >> 2, bj = (g8 >> 1) & 1, nn = g8 & 1;
;         const u32x4 ga = *gate_slot(P, tile, seg, g8), gb = *gate_slot(P, tile, seg + 1, g8);
; #pragma unroll
;         for (int e = 0; e < 8; ++e) {
;             const float rl = (float)((ga[e >> 2] >> (8 * (e & 3))) & 255u) * frcp((float)((gb[e >> 2] >> (8 * (e & 3))) & 255u));
;             const float rh = (float)((ga[2 + (e >> 2)] >> (8 * (e & 3))) & 255u) * frcp((float)((gb[2 + (e >> 2)] >> (8 * (e & 3))) & 255u));
;             acc[ai][bj][e >> 2][nn][e & 3] *= rl;
;             acc[ai][bj][2 + (e >> 2)][nn][e & 3] *= rh;
;         }
;         __builtin_amdgcn_sched_barrier(0);
;     }
; }
	s_nop 1
	v_mov_b64_e32 v[146:147], v[234:235]
	v_mov_b64_e32 v[148:149], v[236:237]
	v_cvt_f32_ubyte0_e32 v59, v148
	v_cvt_f32_ubyte1_e32 v60, v148
	v_cvt_f32_ubyte2_e32 v61, v148
	v_cvt_f32_ubyte0_e32 v58, v146
	v_rcp_iflag_f32_e32 v150, v59
	v_cvt_f32_ubyte1_e32 v59, v146
	v_rcp_iflag_f32_e32 v151, v60
	v_cvt_f32_ubyte2_e32 v60, v146
	v_rcp_iflag_f32_e32 v152, v61
	v_cvt_f32_ubyte3_e32 v61, v146
	v_rcp_iflag_f32_e32 v58, v58
	v_rcp_iflag_f32_e32 v59, v59
	v_rcp_iflag_f32_e32 v60, v60
	v_rcp_iflag_f32_e32 v61, v61
	v_cvt_f32_ubyte3_e32 v146, v148
	v_rcp_iflag_f32_e32 v153, v146
	v_pk_mul_f32 v[58:59], v[58:59], v[192:193]
	v_pk_mul_f32 v[60:61], v[60:61], v[172:173]
	v_pk_mul_f32 v[58:59], v[74:75], v[58:59]
	v_pk_mul_f32 v[60:61], v[76:77], v[60:61]
	v_cvt_f32_ubyte3_e32 v75, v136
	v_cvt_f32_ubyte2_e32 v74, v136
	v_cvt_f32_ubyte1_e32 v77, v136
	v_cvt_f32_ubyte0_e32 v76, v136
	v_pk_mul_f32 v[76:77], v[150:151], v[76:77]
	v_pk_mul_f32 v[74:75], v[152:153], v[74:75]
	v_pk_mul_f32 v[66:67], v[66:67], v[76:77]
	v_pk_mul_f32 v[68:69], v[68:69], v[74:75]
	v_cvt_f32_ubyte0_e32 v74, v147
	v_cvt_f32_ubyte1_e32 v75, v147
	v_cvt_f32_ubyte2_e32 v76, v147
	v_cvt_f32_ubyte3_e32 v77, v147
	v_rcp_iflag_f32_e32 v150, v74
	v_rcp_iflag_f32_e32 v151, v75
	v_rcp_iflag_f32_e32 v146, v76
	v_rcp_iflag_f32_e32 v147, v77
	v_cvt_f32_ubyte0_e32 v74, v149
	v_cvt_f32_ubyte1_e32 v75, v149
	v_cvt_f32_ubyte2_e32 v76, v149
	v_cvt_f32_ubyte3_e32 v77, v149
	v_rcp_iflag_f32_e32 v74, v74
	v_rcp_iflag_f32_e32 v75, v75
	v_rcp_iflag_f32_e32 v76, v76
	v_rcp_iflag_f32_e32 v77, v77
	v_cvt_f32_ubyte3_e32 v149, v135
	v_cvt_f32_ubyte2_e32 v148, v135
	v_cvt_f32_ubyte1_e32 v153, v135
	v_cvt_f32_ubyte0_e32 v152, v135
	v_pk_mul_f32 v[134:135], v[150:151], v[152:153]
	v_pk_mul_f32 v[146:147], v[146:147], v[148:149]
	v_pk_mul_f32 v[70:71], v[70:71], v[134:135]
	v_pk_mul_f32 v[72:73], v[72:73], v[146:147]
	v_cvt_f32_ubyte3_e32 v135, v137
	v_cvt_f32_ubyte2_e32 v134, v137
	v_cvt_f32_ubyte1_e32 v147, v137
	v_cvt_f32_ubyte0_e32 v146, v137
	v_pk_mul_f32 v[74:75], v[74:75], v[146:147]
	v_pk_mul_f32 v[76:77], v[76:77], v[134:135]
	v_pk_mul_f32 v[62:63], v[62:63], v[74:75]
	v_pk_mul_f32 v[64:65], v[64:65], v[76:77]
	v_mov_b32_e32 v74, v162
	s_add_u32 s54, s35, 0x13806000
	v_ashrrev_i32_e32 v75, 31, v74
	v_lshl_add_u64 v[74:75], v[74:75], 4, s[10:11]
	v_mov_b32_e32 v74, v162
	s_addc_u32 s55, vcc_lo, 0
	v_ashrrev_i32_e32 v75, 31, v74
	v_lshl_add_u64 v[74:75], v[74:75], 4, s[54:55]
	s_waitcnt vmcnt(1)
	s_nop 1
	v_mov_b64_e32 v[134:135], v[222:223]
	v_mov_b64_e32 v[136:137], v[224:225]
	v_cvt_f32_ubyte3_e32 v173, v134
	v_cvt_f32_ubyte2_e32 v172, v134
	v_cvt_f32_ubyte1_e32 v193, v134
	v_cvt_f32_ubyte0_e32 v192, v134
	s_waitcnt vmcnt(0)
	s_nop 1
	v_mov_b64_e32 v[146:147], v[238:239]
	v_mov_b64_e32 v[148:149], v[240:241]
	global_load_dwordx4 v[210:213], v[242:243], off
	v_lshl_add_u64 v[242:243], v[242:243], 0, s[0:1]
	global_load_dwordx4 v[226:229], v[244:245], off
	v_lshl_add_u64 v[244:245], v[244:245], 0, s[0:1]
	global_load_dwordx4 v[214:217], v[242:243], off
	v_lshl_add_u64 v[242:243], v[242:243], 0, s[0:1]
	global_load_dwordx4 v[230:233], v[244:245], off
	v_lshl_add_u64 v[244:245], v[244:245], 0, s[0:1]
	global_load_dwordx4 v[218:221], v[242:243], off
	v_lshl_add_u64 v[242:243], v[242:243], 0, s[0:1]
	global_load_dwordx4 v[234:237], v[244:245], off
	v_lshl_add_u64 v[244:245], v[244:245], 0, s[0:1]
	global_load_dwordx4 v[222:225], v[242:243], off
	v_lshl_add_u64 v[242:243], v[242:243], 0, s[0:1]
	global_load_dwordx4 v[238:241], v[244:245], off
	v_lshl_add_u64 v[244:245], v[244:245], 0, s[0:1]
	v_cvt_f32_ubyte0_e32 v75, v148
	v_cvt_f32_ubyte1_e32 v76, v148
	v_cvt_f32_ubyte2_e32 v77, v148
	v_cvt_f32_ubyte0_e32 v74, v146
	v_rcp_iflag_f32_e32 v150, v75
	v_cvt_f32_ubyte1_e32 v75, v146
	v_rcp_iflag_f32_e32 v151, v76
	v_cvt_f32_ubyte2_e32 v76, v146
	v_rcp_iflag_f32_e32 v152, v77
	v_cvt_f32_ubyte3_e32 v77, v146
	v_rcp_iflag_f32_e32 v74, v74
	v_rcp_iflag_f32_e32 v75, v75
	v_rcp_iflag_f32_e32 v76, v76
	v_rcp_iflag_f32_e32 v77, v77
	v_cvt_f32_ubyte3_e32 v146, v148
	v_rcp_iflag_f32_e32 v153, v146
	v_pk_mul_f32 v[74:75], v[74:75], v[192:193]
	v_pk_mul_f32 v[76:77], v[76:77], v[172:173]
	v_pk_mul_f32 v[74:75], v[90:91], v[74:75]
	v_pk_mul_f32 v[76:77], v[92:93], v[76:77]
	v_cvt_f32_ubyte3_e32 v91, v136
	v_cvt_f32_ubyte2_e32 v90, v136
	v_cvt_f32_ubyte1_e32 v93, v136
	v_cvt_f32_ubyte0_e32 v92, v136
	v_pk_mul_f32 v[92:93], v[150:151], v[92:93]
	v_pk_mul_f32 v[90:91], v[152:153], v[90:91]
	v_pk_mul_f32 v[82:83], v[82:83], v[92:93]
	v_pk_mul_f32 v[84:85], v[84:85], v[90:91]
	v_cvt_f32_ubyte0_e32 v90, v147
	v_cvt_f32_ubyte1_e32 v91, v147
	v_cvt_f32_ubyte2_e32 v92, v147
	v_cvt_f32_ubyte3_e32 v93, v147
	v_rcp_iflag_f32_e32 v150, v90
	v_rcp_iflag_f32_e32 v151, v91
	v_rcp_iflag_f32_e32 v146, v92
	v_rcp_iflag_f32_e32 v147, v93
	v_cvt_f32_ubyte0_e32 v90, v149
	v_cvt_f32_ubyte1_e32 v91, v149
	v_cvt_f32_ubyte2_e32 v92, v149
	v_cvt_f32_ubyte3_e32 v93, v149
	v_rcp_iflag_f32_e32 v90, v90
	v_rcp_iflag_f32_e32 v91, v91
	v_rcp_iflag_f32_e32 v92, v92
	v_rcp_iflag_f32_e32 v93, v93
	v_cvt_f32_ubyte3_e32 v149, v135
	v_cvt_f32_ubyte2_e32 v148, v135
	v_cvt_f32_ubyte1_e32 v153, v135
	v_cvt_f32_ubyte0_e32 v152, v135
	v_pk_mul_f32 v[134:135], v[150:151], v[152:153]
	v_pk_mul_f32 v[146:147], v[146:147], v[148:149]
	v_pk_mul_f32 v[86:87], v[86:87], v[134:135]
	v_pk_mul_f32 v[88:89], v[88:89], v[146:147]
	v_cvt_f32_ubyte3_e32 v135, v137
	v_cvt_f32_ubyte2_e32 v134, v137
	v_cvt_f32_ubyte1_e32 v147, v137
	v_cvt_f32_ubyte0_e32 v146, v137
	v_pk_mul_f32 v[90:91], v[90:91], v[146:147]
	v_pk_mul_f32 v[92:93], v[92:93], v[134:135]
	v_pk_mul_f32 v[78:79], v[78:79], v[90:91]
	v_pk_mul_f32 v[80:81], v[80:81], v[92:93]
	v_mov_b32_e32 v90, v162
	s_add_u32 s6, s35, 0x13808000
	v_ashrrev_i32_e32 v91, 31, v90
	v_lshl_add_u64 v[90:91], v[90:91], 4, s[12:13]
	v_mov_b32_e32 v90, v162
	s_addc_u32 s7, vcc_lo, 0
	v_ashrrev_i32_e32 v91, 31, v90
	v_lshl_add_u64 v[90:91], v[90:91], 4, s[6:7]
	s_waitcnt vmcnt(7)
; DI float frcp(float x) { return __builtin_amdgcn_rcpf(x); }
; DI u32x4* gate_slot(const Params& P, int tile, int j, int g8) { return (u32x4*)slotp(P, SL_SK) + ((size_t)(tile * 3 + j) * 8 + g8) * 512 + tid(); }
; DI void merge_scale(const Params& P, int tile, int seg, f32x4 (&acc)[2][2][4][2]) {
; #pragma unroll
;     for (int g8 = 0; g8 < 8; ++g8) {
;         const int ai = g8 >> 2, bj = (g8 >> 1) & 1, nn = g8 & 1;
;         const u32x4 ga = *gate_slot(P, tile, seg, g8), gb = *gate_slot(P, tile, seg + 1, g8);
; #pragma unroll
;         for (int e = 0; e < 8; ++e) {
;             const float rl = (float)((ga[e >> 2] >> (8 * (e & 3))) & 255u) * frcp((float)((gb[e >> 2] >> (8 * (e & 3))) & 255u));
;             const float rh = (float)((ga[2 + (e >> 2)] >> (8 * (e & 3))) & 255u) * frcp((float)((gb[2 + (e >> 2)] >> (8 * (e & 3))) & 255u));
;             acc[ai][bj][e >> 2][nn][e & 3] *= rl;
;             acc[ai][bj][2 + (e >> 2)][nn][e & 3] *= rh;
;         }
;         __builtin_amdgcn_sched_barrier(0);
;     }
; }
	s_nop 1
	v_mov_b64_e32 v[134:135], v[210:211]
	v_mov_b64_e32 v[136:137], v[212:213]
	v_cvt_f32_ubyte3_e32 v173, v134
	v_cvt_f32_ubyte2_e32 v172, v134
	v_cvt_f32_ubyte1_e32 v193, v134
	v_cvt_f32_ubyte0_e32 v192, v134
	s_waitcnt vmcnt(6)
	s_nop 1
	v_mov_b64_e32 v[146:147], v[226:227]
	v_mov_b64_e32 v[148:149], v[228:229]
	v_cvt_f32_ubyte0_e32 v91, v148
	v_cvt_f32_ubyte1_e32 v92, v148
	v_cvt_f32_ubyte2_e32 v93, v148
	v_cvt_f32_ubyte0_e32 v90, v146
	v_rcp_iflag_f32_e32 v150, v91
	v_cvt_f32_ubyte1_e32 v91, v146
	v_rcp_iflag_f32_e32 v151, v92
	v_cvt_f32_ubyte2_e32 v92, v146
	v_rcp_iflag_f32_e32 v152, v93
	v_cvt_f32_ubyte3_e32 v93, v146
	v_rcp_iflag_f32_e32 v90, v90
	v_rcp_iflag_f32_e32 v91, v91
	v_rcp_iflag_f32_e32 v92, v92
	v_rcp_iflag_f32_e32 v93, v93
	v_cvt_f32_ubyte3_e32 v146, v148
	v_rcp_iflag_f32_e32 v153, v146
	v_pk_mul_f32 v[90:91], v[90:91], v[192:193]
	v_pk_mul_f32 v[92:93], v[92:93], v[172:173]
	v_pk_mul_f32 v[90:91], v[106:107], v[90:91]
	v_pk_mul_f32 v[92:93], v[108:109], v[92:93]
	v_cvt_f32_ubyte3_e32 v107, v136
	v_cvt_f32_ubyte2_e32 v106, v136
	v_cvt_f32_ubyte1_e32 v109, v136
	v_cvt_f32_ubyte0_e32 v108, v136
	v_pk_mul_f32 v[108:109], v[150:151], v[108:109]
	v_pk_mul_f32 v[106:107], v[152:153], v[106:107]
	v_pk_mul_f32 v[98:99], v[98:99], v[108:109]
	v_pk_mul_f32 v[100:101], v[100:101], v[106:107]
	v_cvt_f32_ubyte0_e32 v106, v147
	v_cvt_f32_ubyte1_e32 v107, v147
	v_cvt_f32_ubyte2_e32 v108, v147
	v_cvt_f32_ubyte3_e32 v109, v147
	v_rcp_iflag_f32_e32 v150, v106
	v_rcp_iflag_f32_e32 v151, v107
	v_rcp_iflag_f32_e32 v146, v108
	v_rcp_iflag_f32_e32 v147, v109
	v_cvt_f32_ubyte0_e32 v106, v149
	v_cvt_f32_ubyte1_e32 v107, v149
	v_cvt_f32_ubyte2_e32 v108, v149
	v_cvt_f32_ubyte3_e32 v109, v149
	v_rcp_iflag_f32_e32 v106, v106
	v_rcp_iflag_f32_e32 v107, v107
	v_rcp_iflag_f32_e32 v108, v108
	v_rcp_iflag_f32_e32 v109, v109
	v_cvt_f32_ubyte3_e32 v149, v135
	v_cvt_f32_ubyte2_e32 v148, v135
	v_cvt_f32_ubyte1_e32 v153, v135
	v_cvt_f32_ubyte0_e32 v152, v135
	v_pk_mul_f32 v[134:135], v[150:151], v[152:153]
	v_pk_mul_f32 v[146:147], v[146:147], v[148:149]
	v_pk_mul_f32 v[102:103], v[102:103], v[134:135]
	v_pk_mul_f32 v[104:105], v[104:105], v[146:147]
	v_cvt_f32_ubyte3_e32 v135, v137
	v_cvt_f32_ubyte2_e32 v134, v137
	v_cvt_f32_ubyte1_e32 v147, v137
	v_cvt_f32_ubyte0_e32 v146, v137
	v_pk_mul_f32 v[106:107], v[106:107], v[146:147]
	v_pk_mul_f32 v[108:109], v[108:109], v[134:135]
	v_pk_mul_f32 v[94:95], v[94:95], v[106:107]
	v_pk_mul_f32 v[96:97], v[96:97], v[108:109]
	v_mov_b32_e32 v106, v162
	s_add_u32 s10, s35, 0x1380a000
	v_ashrrev_i32_e32 v107, 31, v106
	v_lshl_add_u64 v[106:107], v[106:107], 4, s[16:17]
	v_mov_b32_e32 v106, v162
	s_addc_u32 s11, vcc_lo, 0
	v_ashrrev_i32_e32 v107, 31, v106
	v_lshl_add_u64 v[106:107], v[106:107], 4, s[10:11]
	s_waitcnt vmcnt(5)
	s_nop 1
	v_mov_b64_e32 v[134:135], v[214:215]
	v_mov_b64_e32 v[136:137], v[216:217]
	v_cvt_f32_ubyte3_e32 v173, v134
	v_cvt_f32_ubyte2_e32 v172, v134
	v_cvt_f32_ubyte1_e32 v193, v134
	v_cvt_f32_ubyte0_e32 v192, v134
	s_waitcnt vmcnt(4)
	s_nop 1
	v_mov_b64_e32 v[146:147], v[230:231]
	v_mov_b64_e32 v[148:149], v[232:233]
	v_cvt_f32_ubyte0_e32 v107, v148
	v_cvt_f32_ubyte1_e32 v108, v148
	v_cvt_f32_ubyte2_e32 v109, v148
	v_cvt_f32_ubyte0_e32 v106, v146
	v_rcp_iflag_f32_e32 v150, v107
	v_cvt_f32_ubyte1_e32 v107, v146
	v_rcp_iflag_f32_e32 v151, v108
	v_cvt_f32_ubyte2_e32 v108, v146
	v_rcp_iflag_f32_e32 v152, v109
	v_cvt_f32_ubyte3_e32 v109, v146
	v_rcp_iflag_f32_e32 v106, v106
	v_rcp_iflag_f32_e32 v107, v107
	v_rcp_iflag_f32_e32 v108, v108
	v_rcp_iflag_f32_e32 v109, v109
	v_cvt_f32_ubyte3_e32 v146, v148
	v_rcp_iflag_f32_e32 v153, v146
	v_pk_mul_f32 v[106:107], v[106:107], v[192:193]
	v_pk_mul_f32 v[108:109], v[108:109], v[172:173]
	v_pk_mul_f32 v[106:107], v[122:123], v[106:107]
	v_pk_mul_f32 v[108:109], v[124:125], v[108:109]
	v_cvt_f32_ubyte3_e32 v123, v136
	v_cvt_f32_ubyte2_e32 v122, v136
	v_cvt_f32_ubyte1_e32 v125, v136
	v_cvt_f32_ubyte0_e32 v124, v136
	v_pk_mul_f32 v[124:125], v[150:151], v[124:125]
	v_pk_mul_f32 v[122:123], v[152:153], v[122:123]
	v_pk_mul_f32 v[114:115], v[114:115], v[124:125]
	v_pk_mul_f32 v[116:117], v[116:117], v[122:123]
	v_cvt_f32_ubyte0_e32 v122, v147
	v_cvt_f32_ubyte1_e32 v123, v147
	v_cvt_f32_ubyte2_e32 v124, v147
	v_cvt_f32_ubyte3_e32 v125, v147
	v_rcp_iflag_f32_e32 v150, v122
	v_rcp_iflag_f32_e32 v151, v123
	v_rcp_iflag_f32_e32 v146, v124
	v_rcp_iflag_f32_e32 v147, v125
	v_cvt_f32_ubyte0_e32 v122, v149
	v_cvt_f32_ubyte1_e32 v123, v149
	v_cvt_f32_ubyte2_e32 v124, v149
	v_cvt_f32_ubyte3_e32 v125, v149
	v_rcp_iflag_f32_e32 v122, v122
	v_rcp_iflag_f32_e32 v123, v123
	v_rcp_iflag_f32_e32 v124, v124
	v_rcp_iflag_f32_e32 v125, v125
	v_cvt_f32_ubyte3_e32 v149, v135
	v_cvt_f32_ubyte2_e32 v148, v135
	v_cvt_f32_ubyte1_e32 v153, v135
	v_cvt_f32_ubyte0_e32 v152, v135
	v_pk_mul_f32 v[134:135], v[150:151], v[152:153]
	v_pk_mul_f32 v[146:147], v[146:147], v[148:149]
	v_pk_mul_f32 v[118:119], v[118:119], v[134:135]
	v_pk_mul_f32 v[120:121], v[120:121], v[146:147]
	v_cvt_f32_ubyte3_e32 v135, v137
	v_cvt_f32_ubyte2_e32 v134, v137
	v_cvt_f32_ubyte1_e32 v147, v137
	v_cvt_f32_ubyte0_e32 v146, v137
	v_pk_mul_f32 v[122:123], v[122:123], v[146:147]
	v_pk_mul_f32 v[124:125], v[124:125], v[134:135]
	v_pk_mul_f32 v[110:111], v[110:111], v[122:123]
	v_pk_mul_f32 v[112:113], v[112:113], v[124:125]
	v_mov_b32_e32 v122, v162
	s_add_u32 s12, s35, 0x1380c000
	v_ashrrev_i32_e32 v123, 31, v122
	v_lshl_add_u64 v[122:123], v[122:123], 4, s[20:21]
	v_mov_b32_e32 v122, v162
	s_addc_u32 s13, vcc_lo, 0
	v_ashrrev_i32_e32 v123, 31, v122
	v_lshl_add_u64 v[122:123], v[122:123], 4, s[12:13]
	s_waitcnt vmcnt(3)
; DI float frcp(float x) { return __builtin_amdgcn_rcpf(x); }
; DI u32x4* gate_slot(const Params& P, int tile, int j, int g8) { return (u32x4*)slotp(P, SL_SK) + ((size_t)(tile * 3 + j) * 8 + g8) * 512 + tid(); }
; DI void merge_scale(const Params& P, int tile, int seg, f32x4 (&acc)[2][2][4][2]) {
; #pragma unroll
;     for (int g8 = 0; g8 < 8; ++g8) {
;         const int ai = g8 >> 2, bj = (g8 >> 1) & 1, nn = g8 & 1;
;         const u32x4 ga = *gate_slot(P, tile, seg, g8), gb = *gate_slot(P, tile, seg + 1, g8);
; #pragma unroll
;         for (int e = 0; e < 8; ++e) {
;             const float rl = (float)((ga[e >> 2] >> (8 * (e & 3))) & 255u) * frcp((float)((gb[e >> 2] >> (8 * (e & 3))) & 255u));
;             const float rh = (float)((ga[2 + (e >> 2)] >> (8 * (e & 3))) & 255u) * frcp((float)((gb[2 + (e >> 2)] >> (8 * (e & 3))) & 255u));
;             acc[ai][bj][e >> 2][nn][e & 3] *= rl;
;             acc[ai][bj][2 + (e >> 2)][nn][e & 3] *= rh;
;         }
;         __builtin_amdgcn_sched_barrier(0);
;     }
; }
	s_nop 1
	v_mov_b64_e32 v[134:135], v[218:219]
	v_mov_b64_e32 v[136:137], v[220:221]
	v_cvt_f32_ubyte3_e32 v173, v134
	v_cvt_f32_ubyte2_e32 v172, v134
	v_cvt_f32_ubyte1_e32 v193, v134
	v_cvt_f32_ubyte0_e32 v192, v134
	s_waitcnt vmcnt(2)
	s_nop 1
	v_mov_b64_e32 v[146:147], v[234:235]
	v_mov_b64_e32 v[148:149], v[236:237]
	v_cvt_f32_ubyte0_e32 v123, v148
	v_cvt_f32_ubyte1_e32 v124, v148
	v_cvt_f32_ubyte2_e32 v125, v148
	v_cvt_f32_ubyte0_e32 v122, v146
	v_rcp_iflag_f32_e32 v150, v123
	v_cvt_f32_ubyte1_e32 v123, v146
	v_rcp_iflag_f32_e32 v151, v124
	v_cvt_f32_ubyte2_e32 v124, v146
	v_rcp_iflag_f32_e32 v152, v125
	v_cvt_f32_ubyte3_e32 v125, v146
	v_rcp_iflag_f32_e32 v122, v122
	v_rcp_iflag_f32_e32 v123, v123
	v_rcp_iflag_f32_e32 v124, v124
	v_rcp_iflag_f32_e32 v125, v125
	v_cvt_f32_ubyte3_e32 v146, v148
	v_rcp_iflag_f32_e32 v153, v146
	v_pk_mul_f32 v[122:123], v[122:123], v[192:193]
	v_pk_mul_f32 v[124:125], v[124:125], v[172:173]
	v_pk_mul_f32 v[122:123], v[126:127], v[122:123]
	v_pk_mul_f32 v[124:125], v[128:129], v[124:125]
	v_cvt_f32_ubyte3_e32 v127, v136
	v_cvt_f32_ubyte2_e32 v126, v136
	v_cvt_f32_ubyte1_e32 v129, v136
	v_cvt_f32_ubyte0_e32 v128, v136
	v_pk_mul_f32 v[128:129], v[150:151], v[128:129]
	v_pk_mul_f32 v[126:127], v[152:153], v[126:127]
	v_pk_mul_f32 v[38:39], v[38:39], v[128:129]
	v_pk_mul_f32 v[40:41], v[40:41], v[126:127]
	v_cvt_f32_ubyte0_e32 v126, v147
	v_cvt_f32_ubyte1_e32 v127, v147
	v_cvt_f32_ubyte2_e32 v128, v147
	v_cvt_f32_ubyte3_e32 v129, v147
	v_rcp_iflag_f32_e32 v150, v126
	v_rcp_iflag_f32_e32 v151, v127
	v_rcp_iflag_f32_e32 v146, v128
	v_rcp_iflag_f32_e32 v147, v129
	v_cvt_f32_ubyte0_e32 v126, v149
	v_cvt_f32_ubyte1_e32 v127, v149
	v_cvt_f32_ubyte2_e32 v128, v149
	v_cvt_f32_ubyte3_e32 v129, v149
	v_rcp_iflag_f32_e32 v126, v126
	v_rcp_iflag_f32_e32 v127, v127
	v_rcp_iflag_f32_e32 v128, v128
	v_rcp_iflag_f32_e32 v129, v129
	v_cvt_f32_ubyte3_e32 v149, v135
	v_cvt_f32_ubyte2_e32 v148, v135
	v_cvt_f32_ubyte1_e32 v153, v135
	v_cvt_f32_ubyte0_e32 v152, v135
	v_pk_mul_f32 v[134:135], v[150:151], v[152:153]
	v_pk_mul_f32 v[146:147], v[146:147], v[148:149]
	v_pk_mul_f32 v[34:35], v[34:35], v[134:135]
	v_pk_mul_f32 v[36:37], v[36:37], v[146:147]
	v_cvt_f32_ubyte3_e32 v135, v137
	v_cvt_f32_ubyte2_e32 v134, v137
	v_cvt_f32_ubyte1_e32 v147, v137
	v_cvt_f32_ubyte0_e32 v146, v137
	v_pk_mul_f32 v[126:127], v[126:127], v[146:147]
	v_pk_mul_f32 v[128:129], v[128:129], v[134:135]
	v_pk_mul_f32 v[22:23], v[22:23], v[126:127]
	v_pk_mul_f32 v[24:25], v[24:25], v[128:129]
	v_mov_b32_e32 v126, v162
	s_add_u32 s16, s35, 0x1380e000
	v_ashrrev_i32_e32 v127, 31, v126
	v_lshl_add_u64 v[126:127], v[126:127], 4, s[22:23]
	v_mov_b32_e32 v134, v162
	s_addc_u32 s17, vcc_lo, 0
	v_ashrrev_i32_e32 v135, 31, v134
	v_lshl_add_u64 v[134:135], v[134:135], 4, s[16:17]
	s_waitcnt vmcnt(1)
	s_nop 1
	v_mov_b64_e32 v[126:127], v[222:223]
	v_mov_b64_e32 v[128:129], v[224:225]
	v_cvt_f32_ubyte3_e32 v173, v126
	v_cvt_f32_ubyte2_e32 v172, v126
	v_cvt_f32_ubyte1_e32 v193, v126
	v_cvt_f32_ubyte0_e32 v192, v126
	s_waitcnt vmcnt(0)
	s_nop 1
	v_mov_b64_e32 v[146:147], v[238:239]
	v_mov_b64_e32 v[148:149], v[240:241]
	v_cvt_f32_ubyte0_e32 v135, v148
	v_cvt_f32_ubyte0_e32 v134, v146
	v_rcp_iflag_f32_e32 v136, v135
	v_cvt_f32_ubyte1_e32 v135, v146
	v_cvt_f32_ubyte2_e32 v150, v146
	v_cvt_f32_ubyte2_e32 v151, v148
	v_cvt_f32_ubyte3_e32 v146, v146
	v_rcp_iflag_f32_e32 v134, v134
	v_rcp_iflag_f32_e32 v135, v135
	v_rcp_iflag_f32_e32 v150, v150
	v_rcp_iflag_f32_e32 v152, v151
	v_rcp_iflag_f32_e32 v151, v146
	v_cvt_f32_ubyte1_e32 v137, v148
	v_cvt_f32_ubyte3_e32 v146, v148
	v_rcp_iflag_f32_e32 v137, v137
	v_rcp_iflag_f32_e32 v153, v146
	v_pk_mul_f32 v[134:135], v[134:135], v[192:193]
	v_pk_mul_f32 v[150:151], v[150:151], v[172:173]
	v_pk_mul_f32 v[14:15], v[14:15], v[134:135]
	v_pk_mul_f32 v[16:17], v[16:17], v[150:151]
	v_cvt_f32_ubyte3_e32 v135, v128
	v_cvt_f32_ubyte2_e32 v134, v128
	v_cvt_f32_ubyte1_e32 v151, v128
	v_cvt_f32_ubyte0_e32 v150, v128
	v_cvt_f32_ubyte0_e32 v126, v147
	v_pk_mul_f32 v[136:137], v[136:137], v[150:151]
	v_pk_mul_f32 v[134:135], v[152:153], v[134:135]
	v_rcp_iflag_f32_e32 v150, v126
	v_cvt_f32_ubyte0_e32 v126, v149
	v_pk_mul_f32 v[12:13], v[12:13], v[134:135]
	v_rcp_iflag_f32_e32 v134, v126
	v_cvt_f32_ubyte1_e32 v126, v147
	v_rcp_iflag_f32_e32 v151, v126
	v_cvt_f32_ubyte1_e32 v126, v149
	v_rcp_iflag_f32_e32 v135, v126
	v_cvt_f32_ubyte2_e32 v126, v147
	v_rcp_iflag_f32_e32 v146, v126
	v_cvt_f32_ubyte2_e32 v126, v149
	v_pk_mul_f32 v[10:11], v[10:11], v[136:137]
	v_rcp_iflag_f32_e32 v136, v126
	v_cvt_f32_ubyte3_e32 v126, v147
	v_rcp_iflag_f32_e32 v147, v126
	v_cvt_f32_ubyte3_e32 v126, v149
	v_rcp_iflag_f32_e32 v137, v126
	v_cvt_f32_ubyte3_e32 v149, v127
	v_cvt_f32_ubyte2_e32 v148, v127
	v_cvt_f32_ubyte1_e32 v153, v127
	v_cvt_f32_ubyte0_e32 v152, v127
	v_pk_mul_f32 v[126:127], v[150:151], v[152:153]
	v_pk_mul_f32 v[146:147], v[146:147], v[148:149]
	v_pk_mul_f32 v[6:7], v[6:7], v[126:127]
	v_pk_mul_f32 v[8:9], v[8:9], v[146:147]
	v_cvt_f32_ubyte3_e32 v127, v129
	v_cvt_f32_ubyte2_e32 v126, v129
	v_cvt_f32_ubyte1_e32 v147, v129
	v_cvt_f32_ubyte0_e32 v146, v129
	v_pk_mul_f32 v[128:129], v[134:135], v[146:147]
	v_pk_mul_f32 v[126:127], v[136:137], v[126:127]
	v_pk_mul_f32 v[2:3], v[2:3], v[128:129]
	v_pk_mul_f32 v[4:5], v[4:5], v[126:127]
	s_mov_b32 s23, 14
	s_mov_b64 s[20:21], 0
	s_mov_b64 s[36:37], 0x20080
	s_mov_b64 s[42:43], 0x20100
	s_mov_b64 s[44:45], 0x20180
